# v28: v20 + LayerNorm wave reductions (10 chains: mean/var in LN1 route/no-route, LN2 moe/dense) as DPP quad_perm / row_half_mirror / row_mirror + v_permlane16/32_swap instead of ds_bpermute butterflie
# baseline (speedup 1.0000x reference)
; __device__ __forceinline__ float wave_sum(float v) {
; #pragma unroll
;     for (int o = 1; o < 64; o <<= 1) v += __shfl_xor(v, o);
;     return v;
; template <int MODE, bool ROUTE, int H8> ...
;     ...
;         for (int r = 0; r < 32; ++r) {
;             const int row = row0 + r;
;             f32x4 v[4]; float s = 0.f;
;             float w0 = 1.f, w1 = 0.f;
;             if (MODE == 1) { w0 = __builtin_bit_cast(float, wq0); w1 = __builtin_bit_cast(float, wq1); }
; #pragma unroll
;             for (int jj = 0; jj < 4; ++jj) {
;                 f32x4 x = xq[jj];
;                 if (xin16) x = __builtin_convertvector(__builtin_bit_cast(f16x4_t, xhq[jj]), f32x4);
;                 f32x4 y;
;                 if (MODE == 0) { const u32x2 yw = yq0[jj]; y = (f32x4){bflo(yw.x), bfhi(yw.x), bflo(yw.y), bfhi(yw.y)}; }
;                 else { const u32x2 ya = yq0[jj], yb = yq1[jj];
;                     y = (f32x4){bflo(ya.x), bfhi(ya.x), bflo(ya.y), bfhi(ya.y)} * w0 + (f32x4){bflo(yb.x), bfhi(yb.x), bflo(yb.y), bfhi(yb.y)} * w1; }
;                 v[jj] = x * ALPHA + gt[jj] * y;
;                 s += (v[jj][0] + v[jj][1]) + (v[jj][2] + v[jj][3]);
;             }
;             if (r + 1 < 32) LN_LOAD(r + 1);
;             const float mean = wave_sum(s) * (1.f / D); float s2 = 0.f;
; #pragma unroll
;             for (int jj = 0; jj < 4; ++jj) { v[jj] = v[jj] - mean; s2 += (v[jj][0] * v[jj][0] + v[jj][1] * v[jj][1]) + (v[jj][2] * v[jj][2] + v[jj][3] * v[jj][3]); }
;             const float rstd = 1.0f / sqrtf(wave_sum(s2) * (1.f / D) + LN_EPS);
.LBB0_808:
	v_cvt_f32_f16_e32 v66, v150
	v_cvt_f32_f16_e32 v111, v151
	v_cvt_f32_f16_sdwa v150, v150 dst_sel:DWORD dst_unused:UNUSED_PAD src0_sel:WORD_1
	v_cvt_f32_f16_sdwa v151, v151 dst_sel:DWORD dst_unused:UNUSED_PAD src0_sel:WORD_1
	v_cndmask_b32_e64 v96, v66, v96, s[36:37]
	v_cndmask_b32_e64 v98, v111, v98, s[36:37]
	v_cndmask_b32_e64 v97, v150, v97, s[36:37]
	v_cndmask_b32_e64 v99, v151, v99, s[36:37]
	v_lshlrev_b32_e32 v150, 16, v158
	v_and_b32_e32 v151, 0xffff0000, v158
	v_lshlrev_b32_e32 v158, 16, v159
	v_and_b32_e32 v159, 0xffff0000, v159
	v_pk_mul_f32 v[150:151], v[84:85], v[150:151]
	v_pk_mul_f32 v[158:159], v[86:87], v[158:159]
	v_pk_fma_f32 v[150:151], v[96:97], s[34:35], v[150:151] op_sel_hi:[1,0,1]
	v_pk_fma_f32 v[158:159], v[98:99], s[34:35], v[158:159] op_sel_hi:[1,0,1]
	v_add_f32_e32 v66, v150, v151
	v_add_f32_e32 v96, v158, v159
	v_add_f32_e32 v66, v66, v96
	v_cvt_f32_f16_e32 v96, v152
	v_cvt_f32_f16_e32 v97, v153
	v_cvt_f32_f16_sdwa v98, v152 dst_sel:DWORD dst_unused:UNUSED_PAD src0_sel:WORD_1
	v_cvt_f32_f16_sdwa v99, v153 dst_sel:DWORD dst_unused:UNUSED_PAD src0_sel:WORD_1
	v_cndmask_b32_e64 v92, v96, v92, s[36:37]
	v_cndmask_b32_e64 v94, v97, v94, s[36:37]
	v_cndmask_b32_e64 v93, v98, v93, s[36:37]
	v_cndmask_b32_e64 v95, v99, v95, s[36:37]
	v_lshlrev_b32_e32 v96, 16, v156
	v_and_b32_e32 v97, 0xffff0000, v156
	v_lshlrev_b32_e32 v98, 16, v157
	v_and_b32_e32 v99, 0xffff0000, v157
	v_pk_mul_f32 v[152:153], v[80:81], v[96:97]
	v_pk_mul_f32 v[96:97], v[82:83], v[98:99]
	v_pk_fma_f32 v[98:99], v[92:93], s[34:35], v[152:153] op_sel_hi:[1,0,1]
	v_pk_fma_f32 v[96:97], v[94:95], s[34:35], v[96:97] op_sel_hi:[1,0,1]
	v_add_f32_e32 v92, v98, v99
	v_add_f32_e32 v93, v96, v97
	v_add_f32_e32 v66, 0, v66
	v_add_f32_e32 v92, v92, v93
	v_add_f32_e32 v66, v92, v66
	v_cvt_f32_f16_e32 v92, v148
	v_cvt_f32_f16_e32 v93, v149
	v_cvt_f32_f16_sdwa v94, v148 dst_sel:DWORD dst_unused:UNUSED_PAD src0_sel:WORD_1
	v_cvt_f32_f16_sdwa v95, v149 dst_sel:DWORD dst_unused:UNUSED_PAD src0_sel:WORD_1
	v_cndmask_b32_e64 v92, v92, v88, s[36:37]
	v_cndmask_b32_e64 v88, v93, v90, s[36:37]
	v_cndmask_b32_e64 v93, v94, v89, s[36:37]
	v_cndmask_b32_e64 v89, v95, v91, s[36:37]
	v_lshlrev_b32_e32 v90, 16, v154
	v_and_b32_e32 v91, 0xffff0000, v154
	v_lshlrev_b32_e32 v94, 16, v155
	v_and_b32_e32 v95, 0xffff0000, v155
	v_pk_mul_f32 v[90:91], v[76:77], v[90:91]
	v_pk_mul_f32 v[94:95], v[78:79], v[94:95]
	v_pk_fma_f32 v[90:91], v[92:93], s[34:35], v[90:91] op_sel_hi:[1,0,1]
	v_pk_fma_f32 v[88:89], v[88:89], s[34:35], v[94:95] op_sel_hi:[1,0,1]
	v_add_f32_e32 v92, v90, v91
	v_add_f32_e32 v93, v88, v89
	v_add_f32_e32 v92, v92, v93
	v_add_f32_e32 v66, v92, v66
	v_cvt_f32_f16_e32 v92, v146
	v_cvt_f32_f16_e32 v93, v147
	v_cvt_f32_f16_sdwa v94, v146 dst_sel:DWORD dst_unused:UNUSED_PAD src0_sel:WORD_1
	v_cvt_f32_f16_sdwa v95, v147 dst_sel:DWORD dst_unused:UNUSED_PAD src0_sel:WORD_1
	v_cndmask_b32_e64 v62, v92, v62, s[36:37]
	v_cndmask_b32_e64 v64, v93, v64, s[36:37]
	v_cndmask_b32_e64 v63, v94, v63, s[36:37]
	v_cndmask_b32_e64 v65, v95, v65, s[36:37]
	s_waitcnt vmcnt(3)
	v_lshlrev_b32_e32 v92, 16, v136
	v_and_b32_e32 v93, 0xffff0000, v136
	v_lshlrev_b32_e32 v94, 16, v137
	v_and_b32_e32 v95, 0xffff0000, v137
	v_pk_mul_f32 v[92:93], v[72:73], v[92:93]
	v_pk_mul_f32 v[94:95], v[74:75], v[94:95]
	v_pk_fma_f32 v[62:63], v[62:63], s[34:35], v[92:93] op_sel_hi:[1,0,1]
	v_pk_fma_f32 v[64:65], v[64:65], s[34:35], v[94:95] op_sel_hi:[1,0,1]
	v_add_f32_e32 v92, v62, v63
	v_add_f32_e32 v93, v64, v65
	v_add_f32_e32 v92, v92, v93
	v_add_f32_e32 v66, v92, v66
	s_nop 1
	s_ashr_i32 s61, s60, 31
	s_waitcnt lgkmcnt(0)
	v_add_f32_dpp v66, v66, v66 quad_perm:[1,0,3,2] row_mask:0xf bank_mask:0xf
	s_nop 1
	s_waitcnt lgkmcnt(0)
	v_add_f32_dpp v66, v66, v66 quad_perm:[2,3,0,1] row_mask:0xf bank_mask:0xf
	s_nop 1
	s_waitcnt lgkmcnt(0)
	v_add_f32_dpp v66, v66, v66 row_half_mirror row_mask:0xf bank_mask:0xf
	s_nop 1
	s_waitcnt lgkmcnt(0)
	v_add_f32_dpp v66, v66, v66 row_mirror row_mask:0xf bank_mask:0xf
	v_mov_b32_e32 v92, v66
	s_nop 1
	v_permlane16_swap_b32_e32 v92, v66
	s_waitcnt lgkmcnt(0)
	v_add_f32_e32 v66, v66, v92
	v_mov_b32_e32 v92, v66
	s_nop 1
	v_permlane32_swap_b32_e32 v92, v66
	s_waitcnt lgkmcnt(0)
	v_add_f32_e32 v111, v66, v92
	v_fmamk_f32 v151, v111, 0xba800000, v151
	v_fmac_f32_e32 v150, 0xba800000, v111
	v_fmamk_f32 v159, v111, 0xba800000, v159
	v_fmac_f32_e32 v158, 0xba800000, v111
	v_pk_mul_f32 v[92:93], v[158:159], v[158:159]
	v_pk_mul_f32 v[94:95], v[150:151], v[150:151]
	v_fmamk_f32 v99, v111, 0xba800000, v99
	v_pk_mov_b32 v[136:137], v[94:95], v[92:93] op_sel:[1,0]
	v_mov_b32_e32 v95, v93
	v_fmac_f32_e32 v98, 0xba800000, v111
	v_fmamk_f32 v97, v111, 0xba800000, v97
	v_fmac_f32_e32 v96, 0xba800000, v111
	v_pk_add_f32 v[92:93], v[136:137], v[94:95]
	v_pk_mul_f32 v[94:95], v[96:97], v[96:97]
	v_pk_mul_f32 v[136:137], v[98:99], v[98:99]
	v_fmac_f32_e32 v90, 0xba800000, v111
	v_pk_mov_b32 v[146:147], v[136:137], v[94:95] op_sel:[1,0]
	v_mov_b32_e32 v137, v95
	v_fmamk_f32 v91, v111, 0xba800000, v91
	v_fmac_f32_e32 v88, 0xba800000, v111
	v_mul_f32_e32 v66, v90, v90
	v_pk_add_f32 v[94:95], v[146:147], v[136:137]
	v_fmamk_f32 v89, v111, 0xba800000, v89
	v_pk_fma_f32 v[136:137], v[90:91], v[90:91], v[66:67] op_sel_hi:[1,1,0]
	v_mul_f32_e32 v66, v88, v88
	v_pk_add_f32 v[92:93], v[92:93], v[92:93] op_sel_hi:[0,1]
	v_pk_add_f32 v[94:95], v[94:95], v[94:95] op_sel_hi:[0,1]
	v_pk_fma_f32 v[146:147], v[88:89], v[88:89], v[66:67] op_sel_hi:[1,1,0]
	v_fmamk_f32 v65, v111, 0xba800000, v65
	v_fmac_f32_e32 v64, 0xba800000, v111
	v_fmamk_f32 v63, v111, 0xba800000, v63
	v_fmac_f32_e32 v62, 0xba800000, v111
	v_mul_f32_e32 v136, v62, v62
	v_mul_f32_e32 v146, v63, v63
	v_mul_f32_e32 v92, v64, v64
	v_mul_f32_e32 v94, v65, v65
	v_pk_add_f32 v[136:137], v[136:137], v[146:147]
	v_pk_add_f32 v[92:93], v[92:93], v[94:95]
	s_nop 0
	v_pk_add_f32 v[92:93], v[136:137], v[92:93]
	global_load_dwordx2 v[136:137], v[144:145], off offset:1536
	v_add_f32_e32 v66, v92, v93
	s_nop 1
	s_waitcnt lgkmcnt(0)
; #define LAS __attribute__((address_space(3)))
; __device__ __forceinline__ unsigned pk2(float lo, float hi) { return cvt_pk_bf16(lo, hi); }
; template <int MODE, bool ROUTE, int H8> ...
;     ...
;             const float mean = wave_sum(s) * (1.f / D); float s2 = 0.f;
; #pragma unroll
;             for (int jj = 0; jj < 4; ++jj) { v[jj] = v[jj] - mean; s2 += (v[jj][0] * v[jj][0] + v[jj][1] * v[jj][1]) + (v[jj][2] * v[jj][2] + v[jj][3] * v[jj][3]); }
;             const float rstd = 1.0f / sqrtf(wave_sum(s2) * (1.f / D) + LN_EPS);
;             float* orow = F.out + (size_t)row * D + 4 * F.lane;
;             unsigned long long* h8 = (unsigned long long*)(HB + (size_t)row * D + 4 * F.lane);
;             float lg[NE];
; #pragma unroll
;             for (int e = 0; e < NE; ++e) lg[e] = 0.f;
;             f32x4 hv[4];
; #pragma unroll
;             for (int jj = 0; jj < 4; ++jj) {
;                 const f32x4 xn = v[jj] * rstd * g4[jj] + b4[jj];
;                 if (xout16) __builtin_nontemporal_store(__builtin_bit_cast(u32x2, __builtin_convertvector(xn, f16x4_t)), (u32x2*)(XH + (size_t)row * D + 4 * F.lane + 256 * jj));
;                 else __builtin_nontemporal_store(xn, (f32x4*)(orow + 256 * jj));
;                 if (next_mod) {
;                     const f32x4 h = xn * (1.0f + nsc[jj]) + nsh[jj];
;                     hv[jj] = h;
;                     if (H8 == 0) h8[64 * jj] = (unsigned long long)pk2(h[0], h[1]) | ((unsigned long long)pk2(h[2], h[3]) << 32);
;                     if (ROUTE) {
; #pragma unroll
;                         for (int i = 0; i < 4; ++i) { const LAS f32x4* wp = (const LAS f32x4*)(wr_l + (4 * F.lane + 256 * jj + i) * 8); const f32x4 wa = wp[0], wb = wp[1];
;                             lg[0] += h[i] * wa[0]; lg[1] += h[i] * wa[1]; lg[2] += h[i] * wa[2]; lg[3] += h[i] * wa[3]; lg[4] += h[i] * wb[0]; lg[5] += h[i] * wb[1]; lg[6] += h[i] * wb[2]; lg[7] += h[i] * wb[3]; }
	v_add_f32_dpp v66, v66, v66 quad_perm:[1,0,3,2] row_mask:0xf bank_mask:0xf
	s_nop 1
	s_waitcnt lgkmcnt(0)
	v_add_f32_dpp v66, v66, v66 quad_perm:[2,3,0,1] row_mask:0xf bank_mask:0xf
	s_nop 1
	s_waitcnt lgkmcnt(0)
	v_add_f32_dpp v66, v66, v66 row_half_mirror row_mask:0xf bank_mask:0xf
	s_nop 1
	s_waitcnt lgkmcnt(0)
	v_add_f32_dpp v66, v66, v66 row_mirror row_mask:0xf bank_mask:0xf
	v_mov_b32_e32 v92, v66
	s_nop 1
	v_permlane16_swap_b32_e32 v92, v66
	s_waitcnt lgkmcnt(0)
	v_add_f32_e32 v66, v66, v92
	v_mov_b32_e32 v92, v66
	s_nop 1
	v_permlane32_swap_b32_e32 v92, v66
	s_waitcnt lgkmcnt(0)
	v_add_f32_e32 v66, v66, v92
	v_fmamk_f32 v66, v66, 0x3a800000, v221
	v_mul_f32_e32 v92, 0x4f800000, v66
	v_cmp_gt_f32_e32 vcc, s85, v66
	s_nop 1
	v_cndmask_b32_e32 v66, v66, v92, vcc
	v_sqrt_f32_e32 v92, v66
	s_nop 0
	v_add_u32_e32 v93, -1, v92
	v_fma_f32 v94, -v93, v92, v66
	v_cmp_ge_f32_e64 s[42:43], 0, v94
	v_add_u32_e32 v94, 1, v92
	s_nop 0
	v_cndmask_b32_e64 v93, v92, v93, s[42:43]
	v_fma_f32 v92, -v94, v92, v66
	v_cmp_lt_f32_e64 s[42:43], 0, v92
	s_nop 1
	v_cndmask_b32_e64 v92, v93, v94, s[42:43]
	v_mul_f32_e32 v93, 0x37800000, v92
	v_cndmask_b32_e32 v92, v92, v93, vcc
	v_cmp_class_f32_e32 vcc, v66, v220
	s_lshl_b64 s[42:43], s[60:61], 10
	s_nop 0
	v_cndmask_b32_e32 v66, v92, v66, vcc
	v_div_scale_f32 v92, s[24:25], v66, v66, 1.0
	v_rcp_f32_e32 v93, v92
	s_lshl_b64 s[24:25], s[60:61], 11
	v_lshl_add_u64 v[144:145], v[104:105], 0, s[24:25]
	v_fma_f32 v94, -v92, v93, 1.0
	v_fmac_f32_e32 v93, v94, v93
	v_div_scale_f32 v94, vcc, 1.0, v66, 1.0
	v_mul_f32_e32 v95, v94, v93
	v_fma_f32 v111, -v92, v95, v94
	v_fmac_f32_e32 v95, v111, v93
	v_fma_f32 v92, -v92, v95, v94
	v_div_fmas_f32 v92, v92, v93, v95
	v_div_fixup_f32 v66, v92, v66, 1.0
	v_pk_mul_f32 v[92:93], v[158:159], v[66:67] op_sel_hi:[1,0]
	v_pk_mul_f32 v[94:95], v[150:151], v[66:67] op_sel_hi:[1,0]
	v_pk_fma_f32 v[92:93], v[4:5], v[92:93], v[12:13]
	v_pk_fma_f32 v[94:95], v[2:3], v[94:95], v[10:11]
	v_cvt_pk_f16_f32 v147, v92, v93
	v_cvt_pk_f16_f32 v146, v94, v95
	global_store_dwordx2 v[144:145], v[146:147], off nt
	ds_read_b128 v[146:149], v169
	ds_read_b128 v[150:153], v169 offset:16
	ds_read_b128 v[154:157], v169 offset:32
	ds_read_b128 v[158:161], v169 offset:48
	v_pk_fma_f32 v[94:95], v[132:133], v[94:95], v[68:69]
	v_pk_fma_f32 v[92:93], v[134:135], v[92:93], v[70:71]
	s_waitcnt lgkmcnt(2)
	v_fma_f32 v191, v150, v94, 0
	v_fma_f32 v111, v148, v94, 0
	v_fma_f32 v190, v149, v94, 0
	v_fma_f32 v192, v151, v94, 0
	ds_read_b128 v[148:151], v169 offset:64
	s_waitcnt lgkmcnt(2)
	v_fmac_f32_e32 v111, v156, v95
	v_fmac_f32_e32 v190, v157, v95
	s_waitcnt lgkmcnt(1)
	v_fmac_f32_e32 v191, v158, v95
	v_fmac_f32_e32 v192, v159, v95
	ds_read_b128 v[156:159], v169 offset:80
	v_fma_f32 v193, v152, v94, 0
	v_fma_f32 v194, v153, v94, 0
	s_waitcnt lgkmcnt(1)
	v_fmac_f32_e32 v111, v150, v92
	v_fmac_f32_e32 v190, v151, v92
	ds_read_b128 v[150:153], v169 offset:96
	ds_read_b128 v[170:173], v169 offset:112
	v_fmac_f32_e32 v193, v160, v95
	v_fmac_f32_e32 v194, v161, v95
	s_waitcnt lgkmcnt(2)
	v_fmac_f32_e32 v191, v156, v92
	v_fmac_f32_e32 v192, v157, v92
	v_fmac_f32_e32 v193, v158, v92
	v_fmac_f32_e32 v194, v159, v92
	ds_read_b128 v[156:159], v169 offset:8192
	s_waitcnt lgkmcnt(1)
	v_fmac_f32_e32 v191, v170, v93
	v_fmac_f32_e32 v192, v171, v93
	v_fmac_f32_e32 v193, v172, v93
	v_fmac_f32_e32 v194, v173, v93
	ds_read_b128 v[170:173], v169 offset:8208
	v_pk_mul_f32 v[98:99], v[98:99], v[66:67] op_sel_hi:[1,0]
	v_fmac_f32_e32 v111, v152, v93
	v_pk_fma_f32 v[98:99], v[6:7], v[98:99], v[14:15]
	v_fmac_f32_e32 v190, v153, v93
	v_cvt_pk_f16_f32 v152, v98, v99
	v_pk_fma_f32 v[98:99], v[128:129], v[98:99], v[58:59]
	ds_read_b128 v[174:177], v169 offset:8240
	s_waitcnt lgkmcnt(2)
	v_fmac_f32_e32 v111, v158, v98
	v_fmac_f32_e32 v190, v159, v98
	ds_read_b128 v[158:161], v169 offset:8224
	s_waitcnt lgkmcnt(2)
	v_fmac_f32_e32 v191, v170, v98
	v_fmac_f32_e32 v192, v171, v98
	v_fmac_f32_e32 v193, v172, v98
	v_fmac_f32_e32 v194, v173, v98
	ds_read_b128 v[170:173], v169 offset:8256
	ds_read_b128 v[178:181], v169 offset:8272
	v_pk_mul_f32 v[96:97], v[96:97], v[66:67] op_sel_hi:[1,0]
	v_pk_mul_f32 v[88:89], v[88:89], v[66:67] op_sel_hi:[1,0]
	v_pk_fma_f32 v[96:97], v[8:9], v[96:97], v[16:17]
	v_pk_mul_f32 v[90:91], v[90:91], v[66:67] op_sel_hi:[1,0]
	v_cvt_pk_f16_f32 v153, v96, v97
	global_store_dwordx2 v[144:145], v[152:153], off offset:512 nt
	v_pk_fma_f32 v[96:97], v[130:131], v[96:97], v[60:61]
	s_waitcnt lgkmcnt(2)
	v_fmac_f32_e32 v111, v160, v99
	v_fmac_f32_e32 v190, v161, v99
	v_pk_fma_f32 v[152:153], v[18:19], v[90:91], v[26:27]
	v_pk_fma_f32 v[88:89], v[20:21], v[88:89], v[28:29]
	v_fmac_f32_e32 v191, v174, v99
	v_fmac_f32_e32 v192, v175, v99
	s_waitcnt lgkmcnt(1)
	v_fmac_f32_e32 v111, v172, v96
	v_fmac_f32_e32 v190, v173, v96
	ds_read_b128 v[172:175], v169 offset:8288
	v_cvt_pk_f16_f32 v91, v88, v89
	v_cvt_pk_f16_f32 v90, v152, v153
	global_store_dwordx2 v[144:145], v[90:91], off offset:1024 nt
	v_pk_fma_f32 v[186:187], v[126:127], v[88:89], v[56:57]
	ds_read_b128 v[88:91], v169 offset:16384
	v_fmac_f32_e32 v193, v176, v99
	v_fmac_f32_e32 v194, v177, v99
	s_waitcnt lgkmcnt(2)
	v_fmac_f32_e32 v191, v178, v96
	v_fmac_f32_e32 v192, v179, v96
	ds_read_b128 v[176:179], v169 offset:8304
	s_waitcnt lgkmcnt(2)
	v_fmac_f32_e32 v111, v174, v97
	v_fmac_f32_e32 v190, v175, v97
	v_pk_fma_f32 v[188:189], v[124:125], v[152:153], v[54:55]
	v_fmac_f32_e32 v193, v180, v96
	s_waitcnt lgkmcnt(1)
	v_fmac_f32_e32 v111, v90, v188
	v_fmac_f32_e32 v190, v91, v188
	v_pk_fma_f32 v[90:91], v[146:147], v[94:95], 0 op_sel_hi:[1,0,0]
	v_fmac_f32_e32 v194, v181, v96
	v_pk_fma_f32 v[90:91], v[154:155], v[94:95], v[90:91] op_sel:[0,1,0]
	s_waitcnt lgkmcnt(0)
; #define LAS __attribute__((address_space(3)))
; template <int MODE, bool ROUTE, int H8> ...
;     ...
;                     if (ROUTE) {
; #pragma unroll
;                         for (int i = 0; i < 4; ++i) { const LAS f32x4* wp = (const LAS f32x4*)(wr_l + (4 * F.lane + 256 * jj + i) * 8); const f32x4 wa = wp[0], wb = wp[1];
;                             lg[0] += h[i] * wa[0]; lg[1] += h[i] * wa[1]; lg[2] += h[i] * wa[2]; lg[3] += h[i] * wa[3]; lg[4] += h[i] * wb[0]; lg[5] += h[i] * wb[1]; lg[6] += h[i] * wb[2]; lg[7] += h[i] * wb[3]; }
;                     }
;                 }
;             }
;             if (H8 == 2 && next_mod) {
;                 float am = 0.f;
; #pragma unroll
;                 for (int jj = 0; jj < 4; ++jj) am = fmaxf(fmaxf(am, fmaxf(fabsf(hv[jj][0]), fabsf(hv[jj][1]))), fmaxf(fabsf(hv[jj][2]), fabsf(hv[jj][3])));
;                 h_store_i8(hv, am, (signed char*)HB + (size_t)row * D + 4 * F.lane, (float*)(F.ws + WS_HSC) + row, F.lane);
;             }
;             if (H8 == 1 && next_mod) {
;                 unsigned* q8 = (unsigned*)((signed char*)HB + (size_t)row * D + 4 * F.lane);
; #pragma unroll
;                 for (int jj = 0; jj < 4; ++jj) { int p = pk_fp8(hv[jj][0] * H2_SCALE, hv[jj][1] * H2_SCALE, 0, false);
;                     p = pk_fp8(hv[jj][2] * H2_SCALE, hv[jj][3] * H2_SCALE, p, true); q8[64 * jj] = (unsigned)p; }
;             }
;             if (ROUTE) {
; #pragma unroll
;                 for (int e = 0; e < NE; ++e) lg[e] = wave_sum(lg[e]);
	v_fmac_f32_e32 v191, v176, v97
	v_pk_fma_f32 v[90:91], v[148:149], v[92:93], v[90:91] op_sel_hi:[1,0,1]
	v_fmac_f32_e32 v192, v177, v97
	v_pk_fma_f32 v[90:91], v[150:151], v[92:93], v[90:91] op_sel:[0,1,0]
	v_fmac_f32_e32 v193, v178, v97
	v_pk_fma_f32 v[90:91], v[156:157], v[98:99], v[90:91] op_sel_hi:[1,0,1]
	v_fmac_f32_e32 v194, v179, v97
	ds_read_b128 v[174:177], v169 offset:16400
	ds_read_b128 v[178:181], v169 offset:16416
	ds_read_b128 v[182:185], v169 offset:16432
	v_pk_fma_f32 v[90:91], v[158:159], v[98:99], v[90:91] op_sel:[0,1,0]
	ds_read_b128 v[146:149], v169 offset:16464
	v_pk_fma_f32 v[90:91], v[170:171], v[96:97], v[90:91] op_sel_hi:[1,0,1]
	s_waitcnt lgkmcnt(3)
	v_fmac_f32_e32 v193, v176, v188
	v_pk_fma_f32 v[90:91], v[172:173], v[96:97], v[90:91] op_sel:[0,1,0]
	v_fmac_f32_e32 v194, v177, v188
	v_pk_fma_f32 v[88:89], v[88:89], v[188:189], v[90:91] op_sel_hi:[1,0,1]
	ds_read_b128 v[150:153], v169 offset:16480
	ds_read_b128 v[154:157], v169 offset:16496
	s_waitcnt lgkmcnt(4)
	v_pk_fma_f32 v[170:171], v[178:179], v[188:189], v[88:89] op_sel:[0,1,0]
	ds_read_b128 v[88:91], v169 offset:16448
	v_fmac_f32_e32 v191, v174, v188
	v_fmac_f32_e32 v192, v175, v188
	v_fmac_f32_e32 v111, v180, v189
	v_fmac_f32_e32 v190, v181, v189
	s_waitcnt lgkmcnt(4)
	v_fmac_f32_e32 v193, v184, v189
	v_fmac_f32_e32 v194, v185, v189
	v_pk_mul_f32 v[64:65], v[64:65], v[66:67] op_sel_hi:[1,0]
	v_pk_mul_f32 v[62:63], v[62:63], v[66:67] op_sel_hi:[1,0]
	v_fmac_f32_e32 v191, v182, v189
	v_fmac_f32_e32 v192, v183, v189
	s_waitcnt lgkmcnt(0)
	v_fmac_f32_e32 v111, v186, v90
	v_fmac_f32_e32 v190, v186, v91
	v_fmac_f32_e32 v193, v186, v148
	v_fmac_f32_e32 v194, v186, v149
	v_pk_fma_f32 v[90:91], v[22:23], v[62:63], v[30:31]
	v_pk_fma_f32 v[148:149], v[24:25], v[64:65], v[32:33]
	v_fmac_f32_e32 v191, v186, v146
	v_fmac_f32_e32 v192, v186, v147
	v_cvt_pk_f16_f32 v147, v148, v149
	v_cvt_pk_f16_f32 v146, v90, v91
	ds_read_b128 v[62:65], v169 offset:24576
	global_store_dwordx2 v[144:145], v[146:147], off offset:1536 nt
	ds_read_b128 v[144:147], v169 offset:24592
	v_fmac_f32_e32 v111, v187, v152
	v_fmac_f32_e32 v190, v187, v153
	v_fmac_f32_e32 v191, v187, v154
	v_fmac_f32_e32 v192, v187, v155
	v_fmac_f32_e32 v193, v187, v156
	v_fmac_f32_e32 v194, v187, v157
	ds_read_b128 v[152:155], v169 offset:24608
	ds_read_b128 v[156:159], v169 offset:24624
	v_pk_fma_f32 v[90:91], v[120:121], v[90:91], v[50:51]
	v_pk_fma_f32 v[172:173], v[122:123], v[148:149], v[52:53]
	s_waitcnt lgkmcnt(3)
	v_fmac_f32_e32 v111, v90, v64
	v_fmac_f32_e32 v190, v90, v65
	s_waitcnt lgkmcnt(2)
	v_fmac_f32_e32 v191, v90, v144
	v_fmac_f32_e32 v192, v90, v145
	v_fmac_f32_e32 v193, v90, v146
	v_fmac_f32_e32 v194, v90, v147
	s_waitcnt lgkmcnt(1)
	v_fmac_f32_e32 v111, v91, v154
	v_fmac_f32_e32 v190, v91, v155
	s_waitcnt lgkmcnt(0)
	v_fmac_f32_e32 v191, v91, v156
	ds_read_b128 v[144:147], v169 offset:24640
	v_fmac_f32_e32 v192, v91, v157
	ds_read_b128 v[154:157], v169 offset:24656
	v_mul_f32_e32 v64, 0x41000000, v94
	v_mul_f32_e32 v65, 0x41000000, v95
	v_med3_f32 v64, v64, s80, v227
	v_med3_f32 v65, v65, s80, v227
	s_waitcnt lgkmcnt(0)
	v_fmac_f32_e32 v191, v172, v154
	v_mov_b32_e32 v154, v67
	v_cvt_pk_fp8_f32 v154, v64, v65
	v_mul_f32_e32 v64, 0x41000000, v92
	v_mul_f32_e32 v65, 0x41000000, v93
	v_med3_f32 v64, v64, s80, v227
	v_med3_f32 v65, v65, s80, v227
	v_cvt_pk_fp8_f32 v154, v64, v65 op_sel:[0,0,1]
	v_mul_f32_e32 v64, 0x41000000, v98
	v_mul_f32_e32 v65, 0x41000000, v99
	v_med3_f32 v64, v64, s80, v227
	v_med3_f32 v65, v65, s80, v227
	v_mov_b32_e32 v99, v67
	v_cvt_pk_fp8_f32 v99, v64, v65
	v_mul_f32_e32 v64, 0x41000000, v96
	v_mul_f32_e32 v65, 0x41000000, v97
	v_med3_f32 v64, v64, s80, v227
	v_med3_f32 v65, v65, s80, v227
	v_cvt_pk_fp8_f32 v99, v64, v65 op_sel:[0,0,1]
	v_mul_f32_e32 v64, 0x41000000, v188
	v_mul_f32_e32 v65, 0x41000000, v189
	v_fmac_f32_e32 v192, v172, v155
	v_med3_f32 v64, v64, s80, v227
	v_med3_f32 v65, v65, s80, v227
	v_mov_b32_e32 v155, v67
	v_fmac_f32_e32 v111, v172, v146
	v_fmac_f32_e32 v190, v172, v147
	ds_read_b128 v[146:149], v169 offset:24672
	v_cvt_pk_fp8_f32 v155, v64, v65
	v_pk_fma_f32 v[64:65], v[186:187], v[88:89], v[170:171] op_sel_hi:[0,1,1]
	v_pk_fma_f32 v[64:65], v[186:187], v[150:151], v[64:65] op_sel:[1,0,0]
	v_fmac_f32_e32 v193, v91, v158
	v_pk_fma_f32 v[62:63], v[90:91], v[62:63], v[64:65] op_sel_hi:[0,1,1]
	v_pk_fma_f32 v[62:63], v[90:91], v[152:153], v[62:63] op_sel:[1,0,0]
	v_fmac_f32_e32 v194, v91, v159
	v_pk_fma_f32 v[62:63], v[172:173], v[144:145], v[62:63] op_sel_hi:[0,1,1]
	ds_read_b128 v[158:161], v169 offset:24688
	s_waitcnt lgkmcnt(1)
	v_pk_fma_f32 v[62:63], v[172:173], v[146:147], v[62:63] op_sel:[1,0,0]
	ds_bpermute_b32 v64, v163, v62
	ds_bpermute_b32 v65, v163, v63
	v_mul_f32_e32 v66, 0x41000000, v186
	v_mul_f32_e32 v92, 0x41000000, v187
	v_med3_f32 v66, v66, s80, v227
	v_med3_f32 v88, v92, s80, v227
	s_waitcnt lgkmcnt(0)
	v_pk_add_f32 v[62:63], v[62:63], v[64:65]
	ds_bpermute_b32 v64, v164, v62
	ds_bpermute_b32 v65, v164, v63
	v_fmac_f32_e32 v111, v173, v148
	v_cvt_pk_fp8_f32 v155, v66, v88 op_sel:[0,0,1]
	v_mul_f32_e32 v66, 0x41000000, v90
	v_mul_f32_e32 v88, 0x41000000, v91
	s_waitcnt lgkmcnt(0)
	v_pk_add_f32 v[62:63], v[62:63], v[64:65]
	v_med3_f32 v66, v66, s80, v227
	v_med3_f32 v88, v88, s80, v227
	v_mov_b32_e32 v144, v67
	ds_bpermute_b32 v64, v165, v62
	ds_bpermute_b32 v65, v165, v63
	ds_bpermute_b32 v89, v163, v111
	v_cvt_pk_fp8_f32 v144, v66, v88
	v_mul_f32_e32 v66, 0x41000000, v172
	v_mul_f32_e32 v88, 0x41000000, v173
	v_med3_f32 v66, v66, s80, v227
	v_med3_f32 v88, v88, s80, v227
	s_waitcnt lgkmcnt(1)
; template <int MODE, bool ROUTE, int H8> ...
;     ...
;             if (H8 == 1 && next_mod) {
;                 unsigned* q8 = (unsigned*)((signed char*)HB + (size_t)row * D + 4 * F.lane);
; #pragma unroll
;                 for (int jj = 0; jj < 4; ++jj) { int p = pk_fp8(hv[jj][0] * H2_SCALE, hv[jj][1] * H2_SCALE, 0, false);
;                     p = pk_fp8(hv[jj][2] * H2_SCALE, hv[jj][3] * H2_SCALE, p, true); q8[64 * jj] = (unsigned)p; }
;             }
;             if (ROUTE) {
; #pragma unroll
;                 for (int e = 0; e < NE; ++e) lg[e] = wave_sum(lg[e]);
;                 int e0 = 0; float v0 = lg[0];
; #pragma unroll
;                 for (int e = 1; e < NE; ++e) if (lg[e] > v0) { v0 = lg[e]; e0 = e; }
;                 int e1 = -1; float v1 = -3.0e38f;
; #pragma unroll
;                 for (int e = 0; e < NE; ++e) if (e != e0 && lg[e] > v1) { v1 = lg[e]; e1 = e; }
;                 const float ex = __expf(v1 - v0), inv = 1.0f / (1.0f + ex);
;                 if (F.lane == 0) {
;                     unsigned* rt = route + (size_t)row * 4; rt[0] = (unsigned)e0 | ((unsigned)e1 << 8); rt[1] = __builtin_bit_cast(unsigned, inv); rt[2] = __builtin_bit_cast(unsigned, ex * inv); rt[3] = 0u;
	v_pk_add_f32 v[62:63], v[62:63], v[64:65]
	v_cvt_pk_fp8_f32 v144, v66, v88 op_sel:[0,0,1]
	s_waitcnt lgkmcnt(0)
	v_add_f32_e32 v66, v111, v89
	ds_bpermute_b32 v64, v166, v62
	ds_bpermute_b32 v65, v166, v63
	ds_bpermute_b32 v88, v164, v66
	v_fmac_f32_e32 v190, v173, v149
	v_fmac_f32_e32 v191, v173, v158
	ds_bpermute_b32 v89, v163, v190
	s_waitcnt lgkmcnt(2)
	v_pk_add_f32 v[62:63], v[62:63], v[64:65]
	s_waitcnt lgkmcnt(1)
	v_add_f32_e32 v66, v66, v88
	ds_bpermute_b32 v64, v167, v62
	ds_bpermute_b32 v65, v167, v63
	ds_bpermute_b32 v88, v165, v66
	ds_bpermute_b32 v90, v163, v191
	v_fmac_f32_e32 v193, v172, v156
	v_fmac_f32_e32 v194, v172, v157
	s_waitcnt lgkmcnt(2)
	v_pk_add_f32 v[62:63], v[62:63], v[64:65]
	v_add_f32_e32 v64, v190, v89
	s_waitcnt lgkmcnt(1)
	v_add_f32_e32 v66, v66, v88
	s_waitcnt lgkmcnt(0)
	v_add_f32_e32 v88, v191, v90
	ds_bpermute_b32 v65, v164, v64
	ds_bpermute_b32 v89, v164, v88
	ds_bpermute_b32 v90, v166, v66
	v_fmac_f32_e32 v192, v173, v159
	v_fmac_f32_e32 v193, v173, v160
	s_waitcnt lgkmcnt(2)
	v_add_f32_e32 v65, v64, v65
	s_waitcnt lgkmcnt(1)
	v_add_f32_e32 v88, v88, v89
	ds_bpermute_b32 v91, v165, v65
	ds_bpermute_b32 v89, v165, v88
	s_waitcnt lgkmcnt(2)
	v_add_f32_e32 v66, v66, v90
	ds_bpermute_b32 v92, v167, v66
	v_fmac_f32_e32 v194, v173, v161
	s_waitcnt lgkmcnt(2)
	v_add_f32_e32 v90, v65, v91
	s_waitcnt lgkmcnt(1)
	v_add_f32_e32 v88, v88, v89
	ds_bpermute_b32 v91, v166, v90
	ds_bpermute_b32 v89, v166, v88
	s_waitcnt lgkmcnt(2)
	v_add_f32_e32 v66, v66, v92
	ds_bpermute_b32 v94, v163, v192
	ds_bpermute_b32 v95, v163, v194
	s_waitcnt lgkmcnt(3)
	v_add_f32_e32 v90, v90, v91
	s_waitcnt lgkmcnt(2)
	v_add_f32_e32 v92, v88, v89
	ds_bpermute_b32 v91, v167, v90
	ds_bpermute_b32 v93, v167, v92
	s_waitcnt lgkmcnt(3)
	v_add_f32_e32 v94, v192, v94
	s_waitcnt lgkmcnt(2)
	v_add_f32_e32 v95, v194, v95
	ds_bpermute_b32 v96, v164, v94
	s_waitcnt lgkmcnt(2)
	v_add_f32_e32 v89, v90, v91
	s_waitcnt lgkmcnt(1)
	v_add_f32_e32 v91, v92, v93
	ds_bpermute_b32 v93, v163, v193
	ds_bpermute_b32 v98, v164, v95
	s_waitcnt lgkmcnt(2)
	v_add_f32_e32 v94, v94, v96
	ds_bpermute_b32 v96, v165, v94
	ds_bpermute_b32 v64, v168, v62
	s_waitcnt lgkmcnt(3)
	v_add_f32_e32 v93, v193, v93
	ds_bpermute_b32 v97, v164, v93
	s_waitcnt lgkmcnt(3)
	v_add_f32_e32 v95, v95, v98
	ds_bpermute_b32 v98, v165, v95
	s_waitcnt lgkmcnt(3)
	v_add_f32_e32 v94, v94, v96
	ds_bpermute_b32 v96, v166, v94
	s_waitcnt lgkmcnt(2)
	v_add_f32_e32 v93, v93, v97
	ds_bpermute_b32 v97, v165, v93
	s_waitcnt lgkmcnt(2)
	v_add_f32_e32 v95, v95, v98
	ds_bpermute_b32 v98, v166, v95
	s_waitcnt lgkmcnt(2)
	v_add_f32_e32 v94, v94, v96
	ds_bpermute_b32 v96, v167, v94
	s_waitcnt lgkmcnt(2)
	v_add_f32_e32 v93, v93, v97
	ds_bpermute_b32 v97, v166, v93
	s_waitcnt lgkmcnt(2)
	v_add_f32_e32 v98, v95, v98
	ds_bpermute_b32 v145, v167, v98
	ds_bpermute_b32 v65, v168, v63
	ds_bpermute_b32 v88, v168, v66
	s_waitcnt lgkmcnt(3)
	v_add_f32_e32 v97, v93, v97
	ds_bpermute_b32 v111, v167, v97
	v_add_f32_e32 v93, v94, v96
	ds_bpermute_b32 v90, v168, v89
	ds_bpermute_b32 v92, v168, v91
	ds_bpermute_b32 v94, v168, v93
	s_waitcnt lgkmcnt(3)
	v_add_f32_e32 v95, v97, v111
	v_add_f32_e32 v97, v98, v145
	ds_bpermute_b32 v96, v168, v95
	ds_bpermute_b32 v98, v168, v97
	v_lshl_add_u64 v[148:149], v[108:109], 0, s[42:43]
	global_store_dword v[148:149], v154, off
	global_store_dword v[148:149], v99, off offset:256
	global_store_dword v[148:149], v155, off offset:512
	global_store_dword v[148:149], v144, off offset:768
	s_and_saveexec_b64 s[62:63], s[38:39]
	s_cbranch_execz .LBB0_810
; template <int MODE, bool ROUTE, int H8> ...
;     ...
;             if (ROUTE) {
; #pragma unroll
;                 for (int e = 0; e < NE; ++e) lg[e] = wave_sum(lg[e]);
;                 int e0 = 0; float v0 = lg[0];
; #pragma unroll
;                 for (int e = 1; e < NE; ++e) if (lg[e] > v0) { v0 = lg[e]; e0 = e; }
;                 int e1 = -1; float v1 = -3.0e38f;
; #pragma unroll
;                 for (int e = 0; e < NE; ++e) if (e != e0 && lg[e] > v1) { v1 = lg[e]; e1 = e; }
;                 const float ex = __expf(v1 - v0), inv = 1.0f / (1.0f + ex);
;                 if (F.lane == 0) {
;                     unsigned* rt = route + (size_t)row * 4; rt[0] = (unsigned)e0 | ((unsigned)e1 << 8); rt[1] = __builtin_bit_cast(unsigned, inv); rt[2] = __builtin_bit_cast(unsigned, ex * inv); rt[3] = 0u;
;                     const int p0 = atomicAdd((int*)&lcnt[e0], 1); llist[e0 * 512 + p0] = row * 2;
;                     const int p1 = atomicAdd((int*)&lcnt[e1], 1); llist[e1 * 512 + p1] = row * 2 + 1;
;                 }
	v_pk_add_f32 v[62:63], v[62:63], v[64:65]
	v_add_f32_e32 v66, v66, v88
	v_cmp_gt_f32_e32 vcc, v63, v62
	s_waitcnt lgkmcnt(4)
	v_add_f32_e32 v89, v89, v90
	s_waitcnt lgkmcnt(3)
	v_add_f32_e32 v91, v91, v92
	v_cndmask_b32_e32 v64, v62, v63, vcc
	v_cmp_gt_f32_e64 s[42:43], v66, v64
	s_waitcnt lgkmcnt(2)
	v_add_f32_e32 v93, v93, v94
	v_cndmask_b32_e64 v65, 0, 1, vcc
	v_cndmask_b32_e64 v64, v64, v66, s[42:43]
	v_cmp_gt_f32_e64 s[44:45], v89, v64
	v_cndmask_b32_e64 v65, v65, 2, s[42:43]
	s_waitcnt lgkmcnt(1)
	v_add_f32_e32 v95, v95, v96
	v_cndmask_b32_e64 v64, v64, v89, s[44:45]
	v_cmp_gt_f32_e64 s[46:47], v91, v64
	v_cndmask_b32_e64 v65, v65, 3, s[44:45]
	s_waitcnt lgkmcnt(0)
	v_add_f32_e32 v97, v97, v98
	v_cndmask_b32_e64 v64, v64, v91, s[46:47]
	v_cmp_gt_f32_e64 s[48:49], v93, v64
	v_cndmask_b32_e64 v65, v65, 4, s[46:47]
	v_cmp_nlt_f32_e64 s[54:55], s30, v62
	v_cndmask_b32_e64 v64, v64, v93, s[48:49]
	v_cmp_gt_f32_e64 s[50:51], v95, v64
	v_cndmask_b32_e64 v65, v65, 5, s[48:49]
	s_nop 0
	v_cndmask_b32_e64 v64, v64, v95, s[50:51]
	v_cndmask_b32_e64 v65, v65, 6, s[50:51]
	v_cmp_ngt_f32_e32 vcc, v97, v64
	s_and_b64 s[24:25], s[50:51], vcc
	s_nop 0
	v_cndmask_b32_e32 v88, 7, v65, vcc
	v_cmp_eq_u32_e64 s[52:53], 0, v88
	s_or_b64 s[52:53], s[52:53], s[54:55]
	v_cmp_ne_u32_e64 s[50:51], 1, v88
	v_cndmask_b32_e64 v62, v62, v228, s[52:53]
	v_cmp_gt_f32_e64 s[54:55], v63, v62
	s_and_b64 s[50:51], s[50:51], s[54:55]
	v_cndmask_b32_e64 v62, v62, v63, s[50:51]
	v_cmp_ne_u32_e64 s[48:49], 2, v88
	v_cmp_gt_f32_e64 s[54:55], v66, v62
	s_and_b64 s[48:49], s[48:49], s[54:55]
	v_cndmask_b32_e64 v62, v62, v66, s[48:49]
	v_cmp_ne_u32_e64 s[46:47], 3, v88
	v_cmp_gt_f32_e64 s[54:55], v89, v62
	s_and_b64 s[46:47], s[46:47], s[54:55]
	v_cndmask_b32_e64 v62, v62, v89, s[46:47]
	v_cmp_ne_u32_e64 s[44:45], 4, v88
	v_cmp_gt_f32_e64 s[54:55], v91, v62
	s_and_b64 s[44:45], s[44:45], s[54:55]
	v_cndmask_b32_e64 v62, v62, v91, s[44:45]
	v_cmp_ne_u32_e64 s[42:43], 5, v88
	v_cmp_gt_f32_e64 s[54:55], v93, v62
	s_and_b64 s[42:43], s[42:43], s[54:55]
	v_cndmask_b32_e64 v62, v62, v93, s[42:43]
	v_cmp_ngt_f32_e64 s[54:55], v95, v62
	s_or_b64 s[54:55], s[24:25], s[54:55]
	v_cndmask_b32_e32 v64, v97, v64, vcc
	v_cndmask_b32_e64 v62, v95, v62, s[54:55]
	v_cmp_gt_f32_e64 s[56:57], v97, v62
	s_and_b64 s[56:57], vcc, s[56:57]
	v_cndmask_b32_e64 v63, 0, -1, s[52:53]
	v_cndmask_b32_e64 v62, v62, v97, s[56:57]
	v_sub_f32_e32 v62, v62, v64
	v_mul_f32_e32 v62, 0x3fb8aa3b, v62
	v_exp_f32_e32 v62, v62
	v_cndmask_b32_e64 v63, v63, 1, s[50:51]
	v_cndmask_b32_e64 v63, v63, 2, s[48:49]
	v_cndmask_b32_e64 v63, v63, 3, s[46:47]
	v_add_f32_e32 v64, 1.0, v62
	v_div_scale_f32 v65, s[24:25], v64, v64, 1.0
	v_rcp_f32_e32 v66, v65
	v_cndmask_b32_e64 v63, v63, 4, s[44:45]
	v_cndmask_b32_e64 v63, v63, 5, s[42:43]
	v_cndmask_b32_e64 v63, 6, v63, s[54:55]
	v_fma_f32 v89, -v65, v66, 1.0
	v_fmac_f32_e32 v66, v89, v66
	v_div_scale_f32 v89, vcc, 1.0, v64, 1.0
	v_mul_f32_e32 v90, v89, v66
	v_fma_f32 v91, -v65, v90, v89
	v_fmac_f32_e32 v90, v91, v66
	v_fma_f32 v65, -v65, v90, v89
	v_div_fmas_f32 v65, v65, v66, v90
	s_lshl_b64 s[24:25], s[60:61], 4
	v_cndmask_b32_e64 v63, v63, 7, s[56:57]
	v_div_fixup_f32 v65, v65, v64, 1.0
	s_add_u32 s24, s3, s24
	s_addc_u32 s25, s6, s25
	v_lshl_add_u32 v64, v63, 8, v88
	v_mul_f32_e32 v66, v62, v65
	global_store_dwordx4 v67, v[64:67], s[24:25]
	v_lshl_add_u32 v62, v88, 2, 0
	ds_add_rtn_u32 v64, v62, v1 offset:32768
	v_mul_lo_u32 v65, v88, s31
	s_add_i32 s24, s86, 1
	s_waitcnt lgkmcnt(0)
	v_lshlrev_b32_e32 v64, 2, v64
	v_add3_u32 v62, v62, v65, v64
	v_mov_b32_e32 v64, s86
	ds_write_b32 v62, v64 offset:33024
	v_lshl_add_u32 v62, v63, 2, 0
	ds_add_rtn_u32 v64, v62, v1 offset:32768
	v_mul_lo_u32 v63, v63, s31
	s_waitcnt lgkmcnt(0)
	v_lshlrev_b32_e32 v64, 2, v64
	v_add3_u32 v62, v62, v63, v64
	v_mov_b32_e32 v63, s24
	ds_write_b32 v62, v63 offset:33024

; template <int MODE, bool ROUTE, int H8> ...
;     ...
;             for (int jj = 0; jj < 4; ++jj) {
;                 f32x4 x = xq[jj];
;                 if (xin16) x = __builtin_convertvector(__builtin_bit_cast(f16x4_t, xhq[jj]), f32x4);
;                 f32x4 y;
;                 if (MODE == 0) { const u32x2 yw = yq0[jj]; y = (f32x4){bflo(yw.x), bfhi(yw.x), bflo(yw.y), bfhi(yw.y)}; }
;                 else { const u32x2 ya = yq0[jj], yb = yq1[jj];
;                     y = (f32x4){bflo(ya.x), bfhi(ya.x), bflo(ya.y), bfhi(ya.y)} * w0 + (f32x4){bflo(yb.x), bfhi(yb.x), bflo(yb.y), bfhi(yb.y)} * w1; }
;                 v[jj] = x * ALPHA + gt[jj] * y;
;                 s += (v[jj][0] + v[jj][1]) + (v[jj][2] + v[jj][3]);
;             }
;             if (r + 1 < 32) LN_LOAD(r + 1);
;             const float mean = wave_sum(s) * (1.f / D); float s2 = 0.f;
; #pragma unroll
;             for (int jj = 0; jj < 4; ++jj) { v[jj] = v[jj] - mean; s2 += (v[jj][0] * v[jj][0] + v[jj][1] * v[jj][1]) + (v[jj][2] * v[jj][2] + v[jj][3] * v[jj][3]); }
;             const float rstd = 1.0f / sqrtf(wave_sum(s2) * (1.f / D) + LN_EPS);
.LBB0_812:
	v_cvt_f32_f16_sdwa v63, v113 dst_sel:DWORD dst_unused:UNUSED_PAD src0_sel:WORD_1
	v_cvt_f32_f16_sdwa v65, v112 dst_sel:DWORD dst_unused:UNUSED_PAD src0_sel:WORD_1
	v_cvt_f32_f16_e32 v62, v113
	v_cvt_f32_f16_e32 v64, v112
	s_waitcnt vmcnt(11)
	v_lshlrev_b32_e32 v88, 16, v142
	v_and_b32_e32 v89, 0xffff0000, v142
	s_waitcnt lgkmcnt(4)
	v_lshlrev_b32_e32 v90, 16, v143
	v_and_b32_e32 v91, 0xffff0000, v143
	v_cndmask_b32_e64 v64, v64, v34, s[36:37]
	v_cndmask_b32_e64 v62, v62, v36, s[36:37]
	v_cndmask_b32_e64 v65, v65, v35, s[36:37]
	v_cndmask_b32_e64 v63, v63, v37, s[36:37]
	v_pk_mul_f32 v[84:85], v[84:85], v[88:89]
	v_pk_mul_f32 v[86:87], v[86:87], v[90:91]
	v_pk_fma_f32 v[64:65], v[64:65], s[34:35], v[84:85] op_sel_hi:[1,0,1]
	v_pk_fma_f32 v[62:63], v[62:63], s[34:35], v[86:87] op_sel_hi:[1,0,1]
	v_mov_b32_e32 v86, v64
	v_pk_mov_b32 v[84:85], v[64:65], v[62:63] op_sel:[1,0]
	v_mov_b32_e32 v87, v63
	v_pk_add_f32 v[84:85], v[84:85], v[86:87]
	v_cvt_f32_f16_e32 v87, v115
	v_add_f32_e32 v66, v84, v85
	v_add_f32_e32 v86, 0, v66
	v_cvt_f32_f16_sdwa v66, v115 dst_sel:DWORD dst_unused:UNUSED_PAD src0_sel:WORD_1
	v_cvt_f32_f16_sdwa v85, v114 dst_sel:DWORD dst_unused:UNUSED_PAD src0_sel:WORD_1
	v_cvt_f32_f16_e32 v84, v114
	s_waitcnt vmcnt(10)
	v_lshlrev_b32_e32 v90, 16, v140
	v_and_b32_e32 v91, 0xffff0000, v140
	s_waitcnt lgkmcnt(3)
	v_lshlrev_b32_e32 v92, 16, v141
	v_and_b32_e32 v93, 0xffff0000, v141
	v_cndmask_b32_e64 v84, v84, v38, s[36:37]
	v_cndmask_b32_e64 v88, v87, v40, s[36:37]
	v_cndmask_b32_e64 v85, v85, v39, s[36:37]
	v_cndmask_b32_e64 v89, v66, v41, s[36:37]
	v_pk_mul_f32 v[80:81], v[80:81], v[90:91]
	v_pk_mul_f32 v[82:83], v[82:83], v[92:93]
	v_pk_fma_f32 v[90:91], v[84:85], s[34:35], v[80:81] op_sel_hi:[1,0,1]
	v_pk_fma_f32 v[88:89], v[88:89], s[34:35], v[82:83] op_sel_hi:[1,0,1]
	v_mov_b32_e32 v82, v90
	v_pk_mov_b32 v[80:81], v[90:91], v[88:89] op_sel:[1,0]
	v_mov_b32_e32 v83, v89
	v_pk_add_f32 v[80:81], v[80:81], v[82:83]
	v_cvt_f32_f16_sdwa v66, v117 dst_sel:DWORD dst_unused:UNUSED_PAD src0_sel:WORD_1
	v_pk_add_f32 v[80:81], v[80:81], v[80:81] op_sel:[0,1] op_sel_hi:[1,0]
	v_cvt_f32_f16_e32 v82, v117
	v_cvt_f32_f16_sdwa v81, v116 dst_sel:DWORD dst_unused:UNUSED_PAD src0_sel:WORD_1
	v_cvt_f32_f16_e32 v83, v116
	s_waitcnt vmcnt(9)
	v_lshlrev_b32_e32 v92, 16, v138
	v_and_b32_e32 v93, 0xffff0000, v138
	s_waitcnt lgkmcnt(2)
	v_lshlrev_b32_e32 v94, 16, v139
	v_and_b32_e32 v95, 0xffff0000, v139
	v_cndmask_b32_e64 v84, v83, v42, s[36:37]
	v_cndmask_b32_e64 v82, v82, v44, s[36:37]
	v_cndmask_b32_e64 v85, v81, v43, s[36:37]
	v_cndmask_b32_e64 v83, v66, v45, s[36:37]
	v_pk_mul_f32 v[76:77], v[76:77], v[92:93]
	v_pk_mul_f32 v[78:79], v[78:79], v[94:95]
	v_pk_fma_f32 v[84:85], v[84:85], s[34:35], v[76:77] op_sel_hi:[1,0,1]
	v_pk_fma_f32 v[82:83], v[82:83], s[34:35], v[78:79] op_sel_hi:[1,0,1]
	v_cvt_f32_f16_sdwa v66, v119 dst_sel:DWORD dst_unused:UNUSED_PAD src0_sel:WORD_1
	v_cvt_f32_f16_sdwa v77, v118 dst_sel:DWORD dst_unused:UNUSED_PAD src0_sel:WORD_1
	v_cvt_f32_f16_e32 v76, v119
	v_cvt_f32_f16_e32 v79, v118
	s_waitcnt vmcnt(8) lgkmcnt(1)
	v_lshlrev_b32_e32 v96, 16, v136
	v_and_b32_e32 v97, 0xffff0000, v136
	s_waitcnt lgkmcnt(0)
	v_lshlrev_b32_e32 v98, 16, v137
	v_and_b32_e32 v99, 0xffff0000, v137
	v_cndmask_b32_e64 v94, v79, v46, s[36:37]
	v_cndmask_b32_e64 v76, v76, v48, s[36:37]
	v_cndmask_b32_e64 v95, v77, v47, s[36:37]
	v_cndmask_b32_e64 v77, v66, v49, s[36:37]
	v_pk_mul_f32 v[72:73], v[72:73], v[96:97]
	v_pk_mul_f32 v[74:75], v[74:75], v[98:99]
	v_add_f32_e32 v78, v84, v85
	v_pk_fma_f32 v[76:77], v[76:77], s[34:35], v[74:75] op_sel_hi:[1,0,1]
	v_pk_fma_f32 v[74:75], v[94:95], s[34:35], v[72:73] op_sel_hi:[1,0,1]
	v_add_f32_e32 v92, v82, v83
	v_mov_b32_e32 v87, v74
	v_mov_b32_e32 v81, v75
	v_mov_b32_e32 v79, v76
	v_mov_b32_e32 v93, v77
	v_pk_add_f32 v[72:73], v[86:87], v[80:81]
	v_pk_add_f32 v[78:79], v[78:79], v[92:93]
	s_or_b32 s12, s12, 31
	v_pk_add_f32 v[72:73], v[72:73], v[78:79]
	s_ashr_i32 s13, s12, 31
	v_add_f32_e32 v66, v72, v73
	s_nop 1
	s_waitcnt lgkmcnt(0)
	v_add_f32_dpp v66, v66, v66 quad_perm:[1,0,3,2] row_mask:0xf bank_mask:0xf
	s_nop 1
	s_waitcnt lgkmcnt(0)
	v_add_f32_dpp v66, v66, v66 quad_perm:[2,3,0,1] row_mask:0xf bank_mask:0xf
	s_nop 1
	s_waitcnt lgkmcnt(0)
	v_add_f32_dpp v66, v66, v66 row_half_mirror row_mask:0xf bank_mask:0xf
	s_nop 1
	s_waitcnt lgkmcnt(0)
	v_add_f32_dpp v66, v66, v66 row_mirror row_mask:0xf bank_mask:0xf
	v_mov_b32_e32 v72, v66
	s_nop 1
	v_permlane16_swap_b32_e32 v72, v66
	s_waitcnt lgkmcnt(0)
	v_add_f32_e32 v66, v66, v72
	v_mov_b32_e32 v72, v66
	s_nop 1
	v_permlane32_swap_b32_e32 v72, v66
	s_waitcnt lgkmcnt(0)
	v_add_f32_e32 v92, v66, v72
	v_fmamk_f32 v65, v92, 0xba800000, v65
	v_fmac_f32_e32 v64, 0xba800000, v92
	v_fmamk_f32 v63, v92, 0xba800000, v63
	v_fmac_f32_e32 v62, 0xba800000, v92
	v_pk_mul_f32 v[72:73], v[62:63], v[62:63]
	v_pk_mul_f32 v[78:79], v[64:65], v[64:65]
	v_fmamk_f32 v91, v92, 0xba800000, v91
	v_pk_mov_b32 v[80:81], v[78:79], v[72:73] op_sel:[1,0]
	v_mov_b32_e32 v79, v73
	v_fmac_f32_e32 v90, 0xba800000, v92
	v_fmamk_f32 v89, v92, 0xba800000, v89
	v_fmac_f32_e32 v88, 0xba800000, v92
	v_pk_add_f32 v[72:73], v[80:81], v[78:79]
	v_pk_mul_f32 v[78:79], v[88:89], v[88:89]
	v_pk_mul_f32 v[80:81], v[90:91], v[90:91]
	v_fmac_f32_e32 v84, 0xba800000, v92
	v_pk_mov_b32 v[86:87], v[80:81], v[78:79] op_sel:[1,0]
	v_mov_b32_e32 v81, v79
	v_fmamk_f32 v85, v92, 0xba800000, v85
	v_fmac_f32_e32 v82, 0xba800000, v92
	v_mul_f32_e32 v66, v84, v84
	v_pk_add_f32 v[78:79], v[86:87], v[80:81]
	v_fmamk_f32 v83, v92, 0xba800000, v83
	v_pk_fma_f32 v[80:81], v[84:85], v[84:85], v[66:67] op_sel_hi:[1,1,0]
	v_mul_f32_e32 v66, v82, v82
	v_pk_add_f32 v[72:73], v[72:73], v[72:73] op_sel_hi:[0,1]
	v_pk_add_f32 v[78:79], v[78:79], v[78:79] op_sel_hi:[0,1]
	v_pk_fma_f32 v[86:87], v[82:83], v[82:83], v[66:67] op_sel_hi:[1,1,0]
	v_fmamk_f32 v77, v92, 0xba800000, v77
	v_fmac_f32_e32 v76, 0xba800000, v92
	v_fmamk_f32 v75, v92, 0xba800000, v75
	v_fmac_f32_e32 v74, 0xba800000, v92
	v_mul_f32_e32 v80, v74, v74
	v_mul_f32_e32 v86, v75, v75
	v_mul_f32_e32 v72, v76, v76
	v_mul_f32_e32 v78, v77, v77
	v_pk_add_f32 v[80:81], v[80:81], v[86:87]
	v_pk_add_f32 v[72:73], v[72:73], v[78:79]
	s_nop 0
	v_pk_add_f32 v[72:73], v[80:81], v[72:73]
	s_nop 0
	v_add_f32_e32 v66, v72, v73
	s_nop 1
	s_waitcnt lgkmcnt(0)
; template <int MODE, bool ROUTE, int H8> ...
;     ...
;             const float mean = wave_sum(s) * (1.f / D); float s2 = 0.f;
; #pragma unroll
;             for (int jj = 0; jj < 4; ++jj) { v[jj] = v[jj] - mean; s2 += (v[jj][0] * v[jj][0] + v[jj][1] * v[jj][1]) + (v[jj][2] * v[jj][2] + v[jj][3] * v[jj][3]); }
;             const float rstd = 1.0f / sqrtf(wave_sum(s2) * (1.f / D) + LN_EPS);
;             float* orow = F.out + (size_t)row * D + 4 * F.lane;
;             unsigned long long* h8 = (unsigned long long*)(HB + (size_t)row * D + 4 * F.lane);
;             float lg[NE];
; #pragma unroll
;             for (int e = 0; e < NE; ++e) lg[e] = 0.f;
;             f32x4 hv[4];
; #pragma unroll
;             for (int jj = 0; jj < 4; ++jj) {
;                 const f32x4 xn = v[jj] * rstd * g4[jj] + b4[jj];
;                 if (xout16) __builtin_nontemporal_store(__builtin_bit_cast(u32x2, __builtin_convertvector(xn, f16x4_t)), (u32x2*)(XH + (size_t)row * D + 4 * F.lane + 256 * jj));
;                 else __builtin_nontemporal_store(xn, (f32x4*)(orow + 256 * jj));
;                 if (next_mod) {
;                     const f32x4 h = xn * (1.0f + nsc[jj]) + nsh[jj];
;                     hv[jj] = h;
;                     if (H8 == 0) h8[64 * jj] = (unsigned long long)pk2(h[0], h[1]) | ((unsigned long long)pk2(h[2], h[3]) << 32);
;                     if (ROUTE) {
; #pragma unroll
;                         for (int i = 0; i < 4; ++i) { const LAS f32x4* wp = (const LAS f32x4*)(wr_l + (4 * F.lane + 256 * jj + i) * 8); const f32x4 wa = wp[0], wb = wp[1];
;                             lg[0] += h[i] * wa[0]; lg[1] += h[i] * wa[1]; lg[2] += h[i] * wa[2]; lg[3] += h[i] * wa[3]; lg[4] += h[i] * wb[0]; lg[5] += h[i] * wb[1]; lg[6] += h[i] * wb[2]; lg[7] += h[i] * wb[3]; }
;                     }
;                 }
;             }
;             if (H8 == 2 && next_mod) {
;                 float am = 0.f;
; #pragma unroll
;                 for (int jj = 0; jj < 4; ++jj) am = fmaxf(fmaxf(am, fmaxf(fabsf(hv[jj][0]), fabsf(hv[jj][1]))), fmaxf(fabsf(hv[jj][2]), fabsf(hv[jj][3])));
;                 h_store_i8(hv, am, (signed char*)HB + (size_t)row * D + 4 * F.lane, (float*)(F.ws + WS_HSC) + row, F.lane);
;             }
;             if (H8 == 1 && next_mod) {
;                 unsigned* q8 = (unsigned*)((signed char*)HB + (size_t)row * D + 4 * F.lane);
; #pragma unroll
	v_add_f32_dpp v66, v66, v66 quad_perm:[1,0,3,2] row_mask:0xf bank_mask:0xf
	s_nop 1
	s_waitcnt lgkmcnt(0)
	v_add_f32_dpp v66, v66, v66 quad_perm:[2,3,0,1] row_mask:0xf bank_mask:0xf
	s_nop 1
	s_waitcnt lgkmcnt(0)
	v_add_f32_dpp v66, v66, v66 row_half_mirror row_mask:0xf bank_mask:0xf
	s_nop 1
	s_waitcnt lgkmcnt(0)
	v_add_f32_dpp v66, v66, v66 row_mirror row_mask:0xf bank_mask:0xf
	v_mov_b32_e32 v72, v66
	s_nop 1
	v_permlane16_swap_b32_e32 v72, v66
	s_waitcnt lgkmcnt(0)
	v_add_f32_e32 v66, v66, v72
	v_mov_b32_e32 v72, v66
	s_nop 1
	v_permlane32_swap_b32_e32 v72, v66
	s_waitcnt lgkmcnt(0)
	v_add_f32_e32 v66, v66, v72
	v_fmamk_f32 v66, v66, 0x3a800000, v221
	v_cmp_gt_f32_e32 vcc, s85, v66
	v_mul_f32_e32 v72, 0x4f800000, v66
	s_nop 0
	v_cndmask_b32_e32 v66, v66, v72, vcc
	v_sqrt_f32_e32 v72, v66
	s_nop 0
	v_add_u32_e32 v73, -1, v72
	v_fma_f32 v78, -v73, v72, v66
	v_cmp_ge_f32_e64 s[40:41], 0, v78
	v_add_u32_e32 v78, 1, v72
	s_nop 0
	v_cndmask_b32_e64 v73, v72, v73, s[40:41]
	v_fma_f32 v72, -v78, v72, v66
	v_cmp_lt_f32_e64 s[40:41], 0, v72
	s_nop 1
	v_cndmask_b32_e64 v72, v73, v78, s[40:41]
	v_mul_f32_e32 v73, 0x37800000, v72
	v_cndmask_b32_e32 v72, v72, v73, vcc
	v_cmp_class_f32_e32 vcc, v66, v220
	s_lshl_b64 s[40:41], s[12:13], 10
	s_nop 0
	v_cndmask_b32_e32 v66, v72, v66, vcc
	v_div_scale_f32 v72, s[24:25], v66, v66, 1.0
	v_rcp_f32_e32 v73, v72
	s_lshl_b64 s[24:25], s[12:13], 11
	v_lshl_add_u64 v[86:87], v[104:105], 0, s[24:25]
	v_fma_f32 v78, -v72, v73, 1.0
	v_fmac_f32_e32 v73, v78, v73
	v_div_scale_f32 v78, vcc, 1.0, v66, 1.0
	v_mul_f32_e32 v79, v78, v73
	v_fma_f32 v80, -v72, v79, v78
	v_fmac_f32_e32 v79, v80, v73
	v_fma_f32 v72, -v72, v79, v78
	v_div_fmas_f32 v72, v72, v73, v79
	v_div_fixup_f32 v66, v72, v66, 1.0
	v_pk_mul_f32 v[62:63], v[62:63], v[66:67] op_sel_hi:[1,0]
	v_pk_mul_f32 v[64:65], v[64:65], v[66:67] op_sel_hi:[1,0]
	v_pk_fma_f32 v[62:63], v[4:5], v[62:63], v[12:13]
	v_pk_fma_f32 v[64:65], v[2:3], v[64:65], v[10:11]
	v_cvt_pk_f16_f32 v73, v62, v63
	v_cvt_pk_f16_f32 v72, v64, v65
	global_store_dwordx2 v[86:87], v[72:73], off nt
	v_pk_fma_f32 v[78:79], v[134:135], v[62:63], v[70:71]
	v_pk_fma_f32 v[80:81], v[132:133], v[64:65], v[68:69]
	ds_read_b128 v[62:65], v169
	ds_read_b128 v[132:135], v169 offset:16
	ds_read_b128 v[68:71], v169 offset:32
	ds_read_b128 v[136:139], v169 offset:48
	s_waitcnt lgkmcnt(3)
	v_fma_f32 v97, v64, v80, 0
	v_fma_f32 v96, v65, v80, 0
	s_waitcnt lgkmcnt(2)
	v_fma_f32 v95, v132, v80, 0
	v_fma_f32 v94, v133, v80, 0
	v_fma_f32 v93, v134, v80, 0
	v_fma_f32 v92, v135, v80, 0
	s_waitcnt lgkmcnt(1)
	v_fmac_f32_e32 v97, v70, v81
	v_fmac_f32_e32 v96, v71, v81
	ds_read_b128 v[70:73], v169 offset:64
	ds_read_b128 v[132:135], v169 offset:80
	v_pk_mul_f32 v[64:65], v[88:89], v[66:67] op_sel_hi:[1,0]
	s_waitcnt lgkmcnt(2)
	v_fmac_f32_e32 v95, v136, v81
	v_pk_fma_f32 v[64:65], v[8:9], v[64:65], v[16:17]
	s_waitcnt lgkmcnt(1)
	v_fmac_f32_e32 v97, v72, v78
	v_fmac_f32_e32 v96, v73, v78
	v_pk_mul_f32 v[72:73], v[90:91], v[66:67] op_sel_hi:[1,0]
	v_fmac_f32_e32 v94, v137, v81
	v_pk_fma_f32 v[72:73], v[6:7], v[72:73], v[14:15]
	v_fmac_f32_e32 v93, v138, v81
	v_fmac_f32_e32 v92, v139, v81
	v_cvt_pk_f16_f32 v89, v64, v65
	v_cvt_pk_f16_f32 v88, v72, v73
	s_waitcnt lgkmcnt(0)
	v_fmac_f32_e32 v95, v132, v78
	v_fmac_f32_e32 v94, v133, v78
	v_fmac_f32_e32 v93, v134, v78
	v_fmac_f32_e32 v92, v135, v78
	ds_read_b128 v[132:135], v169 offset:96
	ds_read_b128 v[136:139], v169 offset:112
	global_store_dwordx2 v[86:87], v[88:89], off offset:512 nt
	v_pk_fma_f32 v[60:61], v[130:131], v[64:65], v[60:61]
	v_pk_fma_f32 v[64:65], v[128:129], v[72:73], v[58:59]
	ds_read_b128 v[88:91], v169 offset:8192
	ds_read_b128 v[128:131], v169 offset:8208
	s_waitcnt lgkmcnt(2)
	v_fmac_f32_e32 v95, v136, v79
	v_fmac_f32_e32 v94, v137, v79
	v_fmac_f32_e32 v93, v138, v79
	v_fmac_f32_e32 v92, v139, v79
	v_fmac_f32_e32 v97, v134, v79
	v_fmac_f32_e32 v96, v135, v79
	s_waitcnt lgkmcnt(0)
	v_fmac_f32_e32 v95, v128, v64
	v_fmac_f32_e32 v94, v129, v64
	v_fmac_f32_e32 v93, v130, v64
	v_fmac_f32_e32 v92, v131, v64
	ds_read_b128 v[128:131], v169 offset:8224
	ds_read_b128 v[134:137], v169 offset:8240
	v_fmac_f32_e32 v97, v90, v64
	v_fmac_f32_e32 v96, v91, v64
	v_pk_mul_f32 v[58:59], v[82:83], v[66:67] op_sel_hi:[1,0]
	s_waitcnt lgkmcnt(1)
	v_fmac_f32_e32 v97, v130, v65
	s_waitcnt lgkmcnt(0)
	v_fmac_f32_e32 v95, v134, v65
	v_fmac_f32_e32 v94, v135, v65
	v_fmac_f32_e32 v93, v136, v65
	v_fmac_f32_e32 v92, v137, v65
	ds_read_b128 v[134:137], v169 offset:8256
	ds_read_b128 v[138:141], v169 offset:8272
	v_fmac_f32_e32 v96, v131, v65
	v_pk_mul_f32 v[72:73], v[84:85], v[66:67] op_sel_hi:[1,0]
	v_pk_fma_f32 v[58:59], v[20:21], v[58:59], v[28:29]
	s_waitcnt lgkmcnt(1)
	v_fmac_f32_e32 v97, v136, v60
	v_fmac_f32_e32 v96, v137, v60
	s_waitcnt lgkmcnt(0)
	v_fmac_f32_e32 v95, v138, v60
	v_fmac_f32_e32 v94, v139, v60
	v_fmac_f32_e32 v93, v140, v60
	v_fmac_f32_e32 v92, v141, v60
	ds_read_b128 v[136:139], v169 offset:8288
	ds_read_b128 v[140:143], v169 offset:8304
	v_pk_fma_f32 v[82:83], v[18:19], v[72:73], v[26:27]
	v_cvt_pk_f16_f32 v73, v58, v59
	v_cvt_pk_f16_f32 v72, v82, v83
	global_store_dwordx2 v[86:87], v[72:73], off offset:1024 nt
	s_waitcnt lgkmcnt(1)
	v_fmac_f32_e32 v97, v138, v61
	v_fmac_f32_e32 v96, v139, v61
	s_waitcnt lgkmcnt(0)
	v_fmac_f32_e32 v95, v140, v61
	v_fmac_f32_e32 v94, v141, v61
	v_fmac_f32_e32 v93, v142, v61
	v_fmac_f32_e32 v92, v143, v61
	v_pk_fma_f32 v[72:73], v[126:127], v[58:59], v[56:57]
	v_pk_fma_f32 v[82:83], v[124:125], v[82:83], v[54:55]
	ds_read_b128 v[54:57], v169 offset:16384
	ds_read_b128 v[124:127], v169 offset:16400
	ds_read_b128 v[138:141], v169 offset:16416
	ds_read_b128 v[142:145], v169 offset:16432
	s_waitcnt lgkmcnt(3)
; #define LAS __attribute__((address_space(3)))
; template <int MODE, bool ROUTE, int H8> ...
;     ...
;                     if (ROUTE) {
; #pragma unroll
;                         for (int i = 0; i < 4; ++i) { const LAS f32x4* wp = (const LAS f32x4*)(wr_l + (4 * F.lane + 256 * jj + i) * 8); const f32x4 wa = wp[0], wb = wp[1];
;                             lg[0] += h[i] * wa[0]; lg[1] += h[i] * wa[1]; lg[2] += h[i] * wa[2]; lg[3] += h[i] * wa[3]; lg[4] += h[i] * wb[0]; lg[5] += h[i] * wb[1]; lg[6] += h[i] * wb[2]; lg[7] += h[i] * wb[3]; }
;                     }
;                 }
;             }
;             if (H8 == 2 && next_mod) {
;                 float am = 0.f;
; #pragma unroll
;                 for (int jj = 0; jj < 4; ++jj) am = fmaxf(fmaxf(am, fmaxf(fabsf(hv[jj][0]), fabsf(hv[jj][1]))), fmaxf(fabsf(hv[jj][2]), fabsf(hv[jj][3])));
;                 h_store_i8(hv, am, (signed char*)HB + (size_t)row * D + 4 * F.lane, (float*)(F.ws + WS_HSC) + row, F.lane);
;             }
;             if (H8 == 1 && next_mod) {
;                 unsigned* q8 = (unsigned*)((signed char*)HB + (size_t)row * D + 4 * F.lane);
; #pragma unroll
;                 for (int jj = 0; jj < 4; ++jj) { int p = pk_fp8(hv[jj][0] * H2_SCALE, hv[jj][1] * H2_SCALE, 0, false);
;                     p = pk_fp8(hv[jj][2] * H2_SCALE, hv[jj][3] * H2_SCALE, p, true); q8[64 * jj] = (unsigned)p; }
;             }
;             if (ROUTE) {
; #pragma unroll
;                 for (int e = 0; e < NE; ++e) lg[e] = wave_sum(lg[e]);
	v_fmac_f32_e32 v97, v56, v82
	v_fmac_f32_e32 v96, v57, v82
	v_pk_fma_f32 v[56:57], v[62:63], v[80:81], 0 op_sel_hi:[1,0,0]
	s_waitcnt lgkmcnt(2)
	v_fmac_f32_e32 v95, v124, v82
	v_pk_fma_f32 v[56:57], v[68:69], v[80:81], v[56:57] op_sel:[0,1,0]
	v_fmac_f32_e32 v94, v125, v82
	v_pk_fma_f32 v[56:57], v[70:71], v[78:79], v[56:57] op_sel_hi:[1,0,1]
	v_fmac_f32_e32 v93, v126, v82
	v_pk_fma_f32 v[56:57], v[132:133], v[78:79], v[56:57] op_sel:[0,1,0]
	v_fmac_f32_e32 v92, v127, v82
	v_pk_fma_f32 v[56:57], v[88:89], v[64:65], v[56:57] op_sel_hi:[1,0,1]
	s_waitcnt lgkmcnt(1)
	v_fmac_f32_e32 v97, v140, v83
	v_pk_fma_f32 v[56:57], v[128:129], v[64:65], v[56:57] op_sel:[0,1,0]
	v_fmac_f32_e32 v96, v141, v83
	v_pk_fma_f32 v[56:57], v[134:135], v[60:61], v[56:57] op_sel_hi:[1,0,1]
	s_waitcnt lgkmcnt(0)
	v_fmac_f32_e32 v95, v142, v83
	v_pk_fma_f32 v[56:57], v[136:137], v[60:61], v[56:57] op_sel:[0,1,0]
	v_fmac_f32_e32 v94, v143, v83
	v_pk_fma_f32 v[54:55], v[54:55], v[82:83], v[56:57] op_sel_hi:[1,0,1]
	v_fmac_f32_e32 v93, v144, v83
	v_pk_fma_f32 v[62:63], v[138:139], v[82:83], v[54:55] op_sel:[0,1,0]
	ds_read_b128 v[54:57], v169 offset:16448
	ds_read_b128 v[68:71], v169 offset:16464
	v_fmac_f32_e32 v92, v145, v83
	v_mul_f32_e32 v64, 0x41000000, v64
	v_mul_f32_e32 v65, 0x41000000, v65
	s_waitcnt lgkmcnt(1)
	v_fmac_f32_e32 v97, v72, v56
	v_fmac_f32_e32 v96, v72, v57
	s_waitcnt lgkmcnt(0)
	v_fmac_f32_e32 v95, v72, v68
	v_fmac_f32_e32 v94, v72, v69
	v_fmac_f32_e32 v93, v72, v70
	v_fmac_f32_e32 v92, v72, v71
	ds_read_b128 v[56:59], v169 offset:16480
	ds_read_b128 v[68:71], v169 offset:16496
	v_med3_f32 v64, v64, s80, v227
	v_med3_f32 v65, v65, s80, v227
	v_mul_f32_e32 v60, 0x41000000, v60
	s_waitcnt lgkmcnt(1)
	v_fmac_f32_e32 v97, v73, v58
	v_fmac_f32_e32 v96, v73, v59
	s_waitcnt lgkmcnt(0)
	v_fmac_f32_e32 v95, v73, v68
	v_fmac_f32_e32 v94, v73, v69
	v_pk_mul_f32 v[58:59], v[76:77], v[66:67] op_sel_hi:[1,0]
	v_pk_mul_f32 v[68:69], v[74:75], v[66:67] op_sel_hi:[1,0]
	v_pk_fma_f32 v[58:59], v[24:25], v[58:59], v[32:33]
	v_pk_fma_f32 v[68:69], v[22:23], v[68:69], v[30:31]
	v_fmac_f32_e32 v93, v73, v70
	v_fmac_f32_e32 v92, v73, v71
	v_cvt_pk_f16_f32 v71, v58, v59
	v_cvt_pk_f16_f32 v70, v68, v69
	global_store_dwordx2 v[86:87], v[70:71], off offset:1536 nt
	v_mul_f32_e32 v66, 0x41000000, v80
	v_mul_f32_e32 v70, 0x41000000, v81
	v_med3_f32 v66, v66, s80, v227
	v_med3_f32 v70, v70, s80, v227
	v_mov_b32_e32 v71, v67
	v_cvt_pk_fp8_f32 v71, v66, v70
	v_mul_f32_e32 v66, 0x41000000, v78
	v_mul_f32_e32 v70, 0x41000000, v79
	v_med3_f32 v66, v66, s80, v227
	v_med3_f32 v70, v70, s80, v227
	v_pk_fma_f32 v[58:59], v[122:123], v[58:59], v[52:53]
	v_pk_fma_f32 v[68:69], v[120:121], v[68:69], v[50:51]
	ds_read_b128 v[50:53], v169 offset:24576
	ds_read_b128 v[74:77], v169 offset:24592
	v_cvt_pk_fp8_f32 v71, v66, v70 op_sel:[0,0,1]
	v_mov_b32_e32 v66, v67
	v_cvt_pk_fp8_f32 v66, v64, v65
	v_mul_f32_e32 v61, 0x41000000, v61
	v_med3_f32 v60, v60, s80, v227
	v_med3_f32 v61, v61, s80, v227
	s_waitcnt lgkmcnt(0)
	v_fmac_f32_e32 v95, v68, v74
	v_fmac_f32_e32 v94, v68, v75
	v_fmac_f32_e32 v93, v68, v76
	v_fmac_f32_e32 v92, v68, v77
	ds_read_b128 v[74:77], v169 offset:24608
	ds_read_b128 v[84:87], v169 offset:24624
	v_cvt_pk_fp8_f32 v66, v60, v61 op_sel:[0,0,1]
	v_mul_f32_e32 v60, 0x41000000, v82
	v_mul_f32_e32 v61, 0x41000000, v83
	v_med3_f32 v60, v60, s80, v227
	v_med3_f32 v61, v61, s80, v227
	v_mov_b32_e32 v64, v67
	v_cvt_pk_fp8_f32 v64, v60, v61
	v_mul_f32_e32 v60, 0x41000000, v72
	v_mul_f32_e32 v61, 0x41000000, v73
	s_waitcnt lgkmcnt(0)
	v_fmac_f32_e32 v95, v69, v84
	v_fmac_f32_e32 v94, v69, v85
	v_fmac_f32_e32 v93, v69, v86
	v_fmac_f32_e32 v92, v69, v87
	ds_read_b128 v[84:87], v169 offset:24640
	ds_read_b128 v[88:91], v169 offset:24656
	v_med3_f32 v60, v60, s80, v227
	v_med3_f32 v61, v61, s80, v227
	v_cvt_pk_fp8_f32 v64, v60, v61 op_sel:[0,0,1]
	v_fmac_f32_e32 v97, v68, v52
	v_fmac_f32_e32 v96, v68, v53
	v_fmac_f32_e32 v97, v69, v76
	v_fmac_f32_e32 v96, v69, v77
	v_lshl_add_u64 v[52:53], v[108:109], 0, s[40:41]
	v_mul_f32_e32 v60, 0x41000000, v68
	v_mul_f32_e32 v61, 0x41000000, v69
	s_waitcnt lgkmcnt(1)
	v_fmac_f32_e32 v97, v58, v86
	v_fmac_f32_e32 v96, v58, v87
	s_waitcnt lgkmcnt(0)
	v_fmac_f32_e32 v95, v58, v88
	v_fmac_f32_e32 v94, v58, v89
	ds_read_b128 v[86:89], v169 offset:24672
	ds_read_b128 v[120:123], v169 offset:24688
	global_store_dword v[52:53], v64, off offset:512
	v_med3_f32 v60, v60, s80, v227
	v_med3_f32 v61, v61, s80, v227
	v_mov_b32_e32 v64, v67
	v_cvt_pk_fp8_f32 v64, v60, v61
	v_mul_f32_e32 v60, 0x41000000, v58
	v_mul_f32_e32 v61, 0x41000000, v59
	v_med3_f32 v60, v60, s80, v227
	v_med3_f32 v61, v61, s80, v227
	v_cvt_pk_fp8_f32 v64, v60, v61 op_sel:[0,0,1]
	global_store_dword v[52:53], v71, off
	global_store_dword v[52:53], v66, off offset:256
	v_fmac_f32_e32 v93, v58, v90
	global_store_dword v[52:53], v64, off offset:768
	v_pk_fma_f32 v[52:53], v[72:73], v[54:55], v[62:63] op_sel_hi:[0,1,1]
	v_pk_fma_f32 v[52:53], v[72:73], v[56:57], v[52:53] op_sel:[1,0,0]
	v_fmac_f32_e32 v92, v58, v91
	v_pk_fma_f32 v[50:51], v[68:69], v[50:51], v[52:53] op_sel_hi:[0,1,1]
	v_pk_fma_f32 v[50:51], v[68:69], v[74:75], v[50:51] op_sel:[1,0,0]
	s_waitcnt lgkmcnt(1)
	v_fmac_f32_e32 v97, v59, v88
	v_pk_fma_f32 v[50:51], v[58:59], v[84:85], v[50:51] op_sel_hi:[0,1,1]
	v_fmac_f32_e32 v96, v59, v89
	s_waitcnt lgkmcnt(0)
	v_fmac_f32_e32 v95, v59, v120
	v_fmac_f32_e32 v94, v59, v121
	v_fmac_f32_e32 v93, v59, v122
	v_fmac_f32_e32 v92, v59, v123
	v_pk_fma_f32 v[50:51], v[58:59], v[86:87], v[50:51] op_sel:[1,0,0]
	ds_bpermute_b32 v52, v163, v50
	ds_bpermute_b32 v53, v163, v51
	ds_bpermute_b32 v54, v163, v97
	ds_bpermute_b32 v56, v163, v96
	ds_bpermute_b32 v58, v163, v95
	ds_bpermute_b32 v60, v163, v94
	ds_bpermute_b32 v62, v163, v93
	ds_bpermute_b32 v64, v163, v92
	s_waitcnt lgkmcnt(6)
; __device__ __forceinline__ float wave_sum(float v) {
; #pragma unroll
;     for (int o = 1; o < 64; o <<= 1) v += __shfl_xor(v, o);
;     return v;
; template <int MODE, bool ROUTE, int H8> ...
;     ...
;             if (ROUTE) {
; #pragma unroll
;                 for (int e = 0; e < NE; ++e) lg[e] = wave_sum(lg[e]);
	v_pk_add_f32 v[50:51], v[50:51], v[52:53]
	s_waitcnt lgkmcnt(5)
	v_add_f32_e32 v54, v97, v54
	s_waitcnt lgkmcnt(4)
	v_add_f32_e32 v56, v96, v56
	s_waitcnt lgkmcnt(3)
	v_add_f32_e32 v58, v95, v58
	s_waitcnt lgkmcnt(2)
	v_add_f32_e32 v60, v94, v60
	s_waitcnt lgkmcnt(1)
	v_add_f32_e32 v62, v93, v62
	s_waitcnt lgkmcnt(0)
	v_add_f32_e32 v64, v92, v64
	ds_bpermute_b32 v52, v164, v50
	ds_bpermute_b32 v53, v164, v51
	ds_bpermute_b32 v55, v164, v54
	ds_bpermute_b32 v57, v164, v56
	ds_bpermute_b32 v59, v164, v58
	ds_bpermute_b32 v61, v164, v60
	ds_bpermute_b32 v63, v164, v62
	ds_bpermute_b32 v65, v164, v64
	s_waitcnt lgkmcnt(6)
	v_pk_add_f32 v[50:51], v[50:51], v[52:53]
	s_waitcnt lgkmcnt(5)
	v_add_f32_e32 v54, v54, v55
	s_waitcnt lgkmcnt(4)
	v_add_f32_e32 v56, v56, v57
	s_waitcnt lgkmcnt(3)
	v_add_f32_e32 v58, v58, v59
	s_waitcnt lgkmcnt(2)
	v_add_f32_e32 v60, v60, v61
	s_waitcnt lgkmcnt(1)
	v_add_f32_e32 v62, v62, v63
	s_waitcnt lgkmcnt(0)
	v_add_f32_e32 v64, v64, v65
	ds_bpermute_b32 v52, v165, v50
	ds_bpermute_b32 v53, v165, v51
	ds_bpermute_b32 v55, v165, v54
	ds_bpermute_b32 v57, v165, v56
	ds_bpermute_b32 v59, v165, v58
	ds_bpermute_b32 v61, v165, v60
	ds_bpermute_b32 v63, v165, v62
	ds_bpermute_b32 v65, v165, v64
	s_waitcnt lgkmcnt(6)
	v_pk_add_f32 v[50:51], v[50:51], v[52:53]
	s_waitcnt lgkmcnt(5)
	v_add_f32_e32 v54, v54, v55
	s_waitcnt lgkmcnt(4)
	v_add_f32_e32 v56, v56, v57
	s_waitcnt lgkmcnt(3)
	v_add_f32_e32 v58, v58, v59
	s_waitcnt lgkmcnt(2)
	v_add_f32_e32 v60, v60, v61
	s_waitcnt lgkmcnt(1)
	v_add_f32_e32 v62, v62, v63
	s_waitcnt lgkmcnt(0)
	v_add_f32_e32 v64, v64, v65
	ds_bpermute_b32 v52, v166, v50
	ds_bpermute_b32 v53, v166, v51
	ds_bpermute_b32 v55, v166, v54
	ds_bpermute_b32 v57, v166, v56
	ds_bpermute_b32 v59, v166, v58
	ds_bpermute_b32 v61, v166, v60
	ds_bpermute_b32 v63, v166, v62
	ds_bpermute_b32 v65, v166, v64
	s_waitcnt lgkmcnt(6)
	v_pk_add_f32 v[50:51], v[50:51], v[52:53]
	s_waitcnt lgkmcnt(5)
	v_add_f32_e32 v54, v54, v55
	s_waitcnt lgkmcnt(4)
	v_add_f32_e32 v56, v56, v57
	s_waitcnt lgkmcnt(3)
	v_add_f32_e32 v58, v58, v59
	s_waitcnt lgkmcnt(2)
	v_add_f32_e32 v60, v60, v61
	s_waitcnt lgkmcnt(1)
	v_add_f32_e32 v62, v62, v63
	s_waitcnt lgkmcnt(0)
	v_add_f32_e32 v64, v64, v65
	ds_bpermute_b32 v52, v167, v50
	ds_bpermute_b32 v53, v167, v51
	ds_bpermute_b32 v55, v167, v54
	ds_bpermute_b32 v57, v167, v56
	ds_bpermute_b32 v59, v167, v58
	ds_bpermute_b32 v61, v167, v60
	ds_bpermute_b32 v63, v167, v62
	ds_bpermute_b32 v65, v167, v64
	s_waitcnt lgkmcnt(6)
	v_pk_add_f32 v[50:51], v[50:51], v[52:53]
	s_waitcnt lgkmcnt(5)
	v_add_f32_e32 v54, v54, v55
	s_waitcnt lgkmcnt(4)
	v_add_f32_e32 v56, v56, v57
	s_waitcnt lgkmcnt(3)
	v_add_f32_e32 v58, v58, v59
	s_waitcnt lgkmcnt(2)
	v_add_f32_e32 v60, v60, v61
	s_waitcnt lgkmcnt(1)
	v_add_f32_e32 v62, v62, v63
	s_waitcnt lgkmcnt(0)
	v_add_f32_e32 v64, v64, v65
	ds_bpermute_b32 v52, v168, v50
	ds_bpermute_b32 v53, v168, v51
	ds_bpermute_b32 v55, v168, v54
	ds_bpermute_b32 v57, v168, v56
	ds_bpermute_b32 v59, v168, v58
	ds_bpermute_b32 v61, v168, v60
	ds_bpermute_b32 v63, v168, v62
	ds_bpermute_b32 v65, v168, v64
	s_and_saveexec_b64 s[56:57], s[38:39]
	s_cbranch_execz .LBB0_774
; template <int MODE, bool ROUTE, int H8> ...
;     ...
;                 int e0 = 0; float v0 = lg[0];
; #pragma unroll
;                 for (int e = 1; e < NE; ++e) if (lg[e] > v0) { v0 = lg[e]; e0 = e; }
;                 int e1 = -1; float v1 = -3.0e38f;
; #pragma unroll
;                 for (int e = 0; e < NE; ++e) if (e != e0 && lg[e] > v1) { v1 = lg[e]; e1 = e; }
;                 const float ex = __expf(v1 - v0), inv = 1.0f / (1.0f + ex);
;                 if (F.lane == 0) {
;                     unsigned* rt = route + (size_t)row * 4; rt[0] = (unsigned)e0 | ((unsigned)e1 << 8); rt[1] = __builtin_bit_cast(unsigned, inv); rt[2] = __builtin_bit_cast(unsigned, ex * inv); rt[3] = 0u;
;                     const int p0 = atomicAdd((int*)&lcnt[e0], 1); llist[e0 * 512 + p0] = row * 2;
;                     const int p1 = atomicAdd((int*)&lcnt[e1], 1); llist[e1 * 512 + p1] = row * 2 + 1;
;                 }
	s_waitcnt lgkmcnt(6)
	v_pk_add_f32 v[50:51], v[50:51], v[52:53]
	s_waitcnt lgkmcnt(5)
	v_add_f32_e32 v54, v54, v55
	v_cmp_gt_f32_e32 vcc, v51, v50
	s_waitcnt lgkmcnt(4)
	v_add_f32_e32 v56, v56, v57
	s_waitcnt lgkmcnt(3)
	v_add_f32_e32 v58, v58, v59
	v_cndmask_b32_e32 v52, v50, v51, vcc
	v_cmp_gt_f32_e64 s[40:41], v54, v52
	s_waitcnt lgkmcnt(2)
	v_add_f32_e32 v60, v60, v61
	v_cndmask_b32_e64 v53, 0, 1, vcc
	v_cndmask_b32_e64 v52, v52, v54, s[40:41]
	v_cmp_gt_f32_e64 s[42:43], v56, v52
	v_cndmask_b32_e64 v53, v53, 2, s[40:41]
	s_waitcnt lgkmcnt(1)
	v_add_f32_e32 v62, v62, v63
	v_cndmask_b32_e64 v52, v52, v56, s[42:43]
	v_cmp_gt_f32_e64 s[44:45], v58, v52
	v_cndmask_b32_e64 v53, v53, 3, s[42:43]
	s_waitcnt lgkmcnt(0)
	v_add_f32_e32 v64, v64, v65
	v_cndmask_b32_e64 v52, v52, v58, s[44:45]
	v_cmp_gt_f32_e64 s[46:47], v60, v52
	v_cndmask_b32_e64 v53, v53, 4, s[44:45]
	v_cmp_nlt_f32_e64 s[52:53], s30, v50
	v_cndmask_b32_e64 v52, v52, v60, s[46:47]
	v_cmp_gt_f32_e64 s[48:49], v62, v52
	v_cndmask_b32_e64 v53, v53, 5, s[46:47]
	s_nop 0
	v_cndmask_b32_e64 v52, v52, v62, s[48:49]
	v_cndmask_b32_e64 v53, v53, 6, s[48:49]
	v_cmp_ngt_f32_e32 vcc, v64, v52
	s_and_b64 s[24:25], s[48:49], vcc
	s_nop 0
	v_cndmask_b32_e32 v53, 7, v53, vcc
	v_cmp_eq_u32_e64 s[50:51], 0, v53
	s_or_b64 s[50:51], s[50:51], s[52:53]
	v_cmp_ne_u32_e64 s[48:49], 1, v53
	v_cndmask_b32_e64 v50, v50, v228, s[50:51]
	v_cmp_gt_f32_e64 s[52:53], v51, v50
	s_and_b64 s[48:49], s[48:49], s[52:53]
	v_cndmask_b32_e64 v50, v50, v51, s[48:49]
	v_cmp_ne_u32_e64 s[46:47], 2, v53
	v_cmp_gt_f32_e64 s[52:53], v54, v50
	s_and_b64 s[46:47], s[46:47], s[52:53]
	v_cndmask_b32_e64 v50, v50, v54, s[46:47]
	v_cmp_ne_u32_e64 s[44:45], 3, v53
	v_cmp_gt_f32_e64 s[52:53], v56, v50
	s_and_b64 s[44:45], s[44:45], s[52:53]
	v_cndmask_b32_e64 v50, v50, v56, s[44:45]
	v_cmp_ne_u32_e64 s[42:43], 4, v53
	v_cmp_gt_f32_e64 s[52:53], v58, v50
	s_and_b64 s[42:43], s[42:43], s[52:53]
	v_cndmask_b32_e64 v50, v50, v58, s[42:43]
	v_cmp_ne_u32_e64 s[40:41], 5, v53
	v_cmp_gt_f32_e64 s[52:53], v60, v50
	s_and_b64 s[40:41], s[40:41], s[52:53]
	v_cndmask_b32_e64 v50, v50, v60, s[40:41]
	v_cmp_ngt_f32_e64 s[52:53], v62, v50
	s_or_b64 s[52:53], s[24:25], s[52:53]
	v_cndmask_b32_e32 v52, v64, v52, vcc
	v_cndmask_b32_e64 v50, v62, v50, s[52:53]
	v_cmp_gt_f32_e64 s[54:55], v64, v50
	s_and_b64 s[54:55], vcc, s[54:55]
	v_cndmask_b32_e64 v51, 0, -1, s[50:51]
	v_cndmask_b32_e64 v50, v50, v64, s[54:55]
	v_sub_f32_e32 v50, v50, v52
	v_mul_f32_e32 v50, 0x3fb8aa3b, v50
	v_exp_f32_e32 v50, v50
	v_cndmask_b32_e64 v51, v51, 1, s[48:49]
	v_cndmask_b32_e64 v51, v51, 2, s[46:47]
	v_cndmask_b32_e64 v51, v51, 3, s[44:45]
	v_add_f32_e32 v52, 1.0, v50
	v_div_scale_f32 v54, s[24:25], v52, v52, 1.0
	v_rcp_f32_e32 v55, v54
	v_cndmask_b32_e64 v51, v51, 4, s[42:43]
	v_cndmask_b32_e64 v51, v51, 5, s[40:41]
	v_cndmask_b32_e64 v51, 6, v51, s[52:53]
	v_fma_f32 v56, -v54, v55, 1.0
	v_fmac_f32_e32 v55, v56, v55
	v_div_scale_f32 v56, vcc, 1.0, v52, 1.0
	v_mul_f32_e32 v57, v56, v55
	v_fma_f32 v58, -v54, v57, v56
	v_fmac_f32_e32 v57, v58, v55
	v_fma_f32 v54, -v54, v57, v56
	v_div_fmas_f32 v54, v54, v55, v57
	s_lshl_b64 s[24:25], s[12:13], 4
	v_cndmask_b32_e64 v51, v51, 7, s[54:55]
	v_div_fixup_f32 v65, v54, v52, 1.0
	s_add_u32 s24, s3, s24
	s_addc_u32 s25, s6, s25
	v_lshl_add_u32 v64, v51, 8, v53
	v_mul_f32_e32 v66, v50, v65
	global_store_dwordx4 v67, v[64:67], s[24:25]
	v_lshl_add_u32 v50, v53, 2, 0
	ds_add_rtn_u32 v52, v50, v1 offset:32768
	s_lshl_b32 s12, s12, 1
	v_mul_lo_u32 v53, v53, s31
	s_waitcnt lgkmcnt(0)
	v_lshlrev_b32_e32 v52, 2, v52
	v_add3_u32 v50, v50, v53, v52
	v_mov_b32_e32 v52, s12
	ds_write_b32 v50, v52 offset:33024
	v_lshl_add_u32 v50, v51, 2, 0
	ds_add_rtn_u32 v52, v50, v1 offset:32768
	s_or_b32 s12, s12, 1
	v_mul_lo_u32 v51, v51, s31
	s_waitcnt lgkmcnt(0)
	v_lshlrev_b32_e32 v52, 2, v52
	v_add3_u32 v50, v50, v51, v52
	v_mov_b32_e32 v51, s12
	ds_write_b32 v50, v51 offset:33024
	s_branch .LBB0_774

; template <int MODE, bool ROUTE, int H8> ...
;     ...
;             for (int jj = 0; jj < 4; ++jj) {
;                 f32x4 x = xq[jj];
;                 if (xin16) x = __builtin_convertvector(__builtin_bit_cast(f16x4_t, xhq[jj]), f32x4);
;                 f32x4 y;
;                 if (MODE == 0) { const u32x2 yw = yq0[jj]; y = (f32x4){bflo(yw.x), bfhi(yw.x), bflo(yw.y), bfhi(yw.y)}; }
;                 else { const u32x2 ya = yq0[jj], yb = yq1[jj];
;                     y = (f32x4){bflo(ya.x), bfhi(ya.x), bflo(ya.y), bfhi(ya.y)} * w0 + (f32x4){bflo(yb.x), bfhi(yb.x), bflo(yb.y), bfhi(yb.y)} * w1; }
;                 v[jj] = x * ALPHA + gt[jj] * y;
;                 s += (v[jj][0] + v[jj][1]) + (v[jj][2] + v[jj][3]);
;             }
;             if (r + 1 < 32) LN_LOAD(r + 1);
;             const float mean = wave_sum(s) * (1.f / D); float s2 = 0.f;
; #pragma unroll
;             for (int jj = 0; jj < 4; ++jj) { v[jj] = v[jj] - mean; s2 += (v[jj][0] * v[jj][0] + v[jj][1] * v[jj][1]) + (v[jj][2] * v[jj][2] + v[jj][3] * v[jj][3]); }
;             const float rstd = 1.0f / sqrtf(wave_sum(s2) * (1.f / D) + LN_EPS);
.LBB0_868:
	v_cvt_f32_f16_e32 v156, v138
	v_cvt_f32_f16_e32 v157, v139
	v_cvt_f32_f16_sdwa v138, v138 dst_sel:DWORD dst_unused:UNUSED_PAD src0_sel:WORD_1
	v_cvt_f32_f16_sdwa v139, v139 dst_sel:DWORD dst_unused:UNUSED_PAD src0_sel:WORD_1
	v_cndmask_b32_e64 v88, v156, v88, s[36:37]
	v_cndmask_b32_e64 v90, v157, v90, s[36:37]
	v_cndmask_b32_e64 v89, v138, v89, s[36:37]
	v_cndmask_b32_e64 v91, v139, v91, s[36:37]
	v_lshlrev_b32_e32 v138, 16, v146
	v_and_b32_e32 v139, 0xffff0000, v146
	v_lshlrev_b32_e32 v146, 16, v147
	v_and_b32_e32 v147, 0xffff0000, v147
	v_pk_mul_f32 v[138:139], v[40:41], v[138:139]
	v_pk_mul_f32 v[146:147], v[42:43], v[146:147]
	v_pk_fma_f32 v[88:89], v[88:89], s[34:35], v[138:139] op_sel_hi:[1,0,1]
	v_pk_fma_f32 v[90:91], v[90:91], s[34:35], v[146:147] op_sel_hi:[1,0,1]
	v_add_f32_e32 v138, v88, v89
	v_add_f32_e32 v139, v90, v91
	v_add_f32_e32 v138, v138, v139
	v_add_f32_e32 v146, 0, v138
	v_cvt_f32_f16_e32 v138, v140
	v_cvt_f32_f16_e32 v139, v141
	v_cvt_f32_f16_sdwa v140, v140 dst_sel:DWORD dst_unused:UNUSED_PAD src0_sel:WORD_1
	v_cvt_f32_f16_sdwa v141, v141 dst_sel:DWORD dst_unused:UNUSED_PAD src0_sel:WORD_1
	v_cndmask_b32_e64 v84, v138, v84, s[36:37]
	v_cndmask_b32_e64 v86, v139, v86, s[36:37]
	v_cndmask_b32_e64 v85, v140, v85, s[36:37]
	v_cndmask_b32_e64 v87, v141, v87, s[36:37]
	v_lshlrev_b32_e32 v138, 16, v150
	v_and_b32_e32 v139, 0xffff0000, v150
	v_lshlrev_b32_e32 v140, 16, v151
	v_and_b32_e32 v141, 0xffff0000, v151
	v_pk_mul_f32 v[138:139], v[52:53], v[138:139]
	v_pk_mul_f32 v[140:141], v[54:55], v[140:141]
	v_pk_fma_f32 v[84:85], v[84:85], s[34:35], v[138:139] op_sel_hi:[1,0,1]
	v_pk_fma_f32 v[86:87], v[86:87], s[34:35], v[140:141] op_sel_hi:[1,0,1]
	v_add_f32_e32 v138, v84, v85
	v_add_f32_e32 v139, v86, v87
	v_add_f32_e32 v138, v138, v139
	v_add_f32_e32 v146, v138, v146
	v_cvt_f32_f16_e32 v138, v142
	v_cvt_f32_f16_e32 v139, v143
	v_cvt_f32_f16_sdwa v140, v142 dst_sel:DWORD dst_unused:UNUSED_PAD src0_sel:WORD_1
	v_cvt_f32_f16_sdwa v141, v143 dst_sel:DWORD dst_unused:UNUSED_PAD src0_sel:WORD_1
	v_cndmask_b32_e64 v80, v138, v80, s[36:37]
	v_cndmask_b32_e64 v82, v139, v82, s[36:37]
	v_cndmask_b32_e64 v81, v140, v81, s[36:37]
	v_cndmask_b32_e64 v83, v141, v83, s[36:37]
	v_lshlrev_b32_e32 v138, 16, v152
	v_and_b32_e32 v139, 0xffff0000, v152
	v_lshlrev_b32_e32 v140, 16, v153
	v_and_b32_e32 v141, 0xffff0000, v153
	v_pk_mul_f32 v[138:139], v[56:57], v[138:139]
	v_pk_mul_f32 v[140:141], v[58:59], v[140:141]
	v_pk_fma_f32 v[80:81], v[80:81], s[34:35], v[138:139] op_sel_hi:[1,0,1]
	v_pk_fma_f32 v[82:83], v[82:83], s[34:35], v[140:141] op_sel_hi:[1,0,1]
	v_add_f32_e32 v138, v80, v81
	v_add_f32_e32 v139, v82, v83
	v_add_f32_e32 v138, v138, v139
	v_add_f32_e32 v142, v138, v146
	v_cvt_f32_f16_e32 v138, v148
	v_cvt_f32_f16_e32 v139, v149
	v_cvt_f32_f16_sdwa v140, v148 dst_sel:DWORD dst_unused:UNUSED_PAD src0_sel:WORD_1
	v_cvt_f32_f16_sdwa v141, v149 dst_sel:DWORD dst_unused:UNUSED_PAD src0_sel:WORD_1
	v_cndmask_b32_e64 v12, v138, v12, s[36:37]
	v_cndmask_b32_e64 v14, v139, v14, s[36:37]
	v_cndmask_b32_e64 v13, v140, v13, s[36:37]
	v_cndmask_b32_e64 v15, v141, v15, s[36:37]
	v_lshlrev_b32_e32 v138, 16, v154
	v_and_b32_e32 v139, 0xffff0000, v154
	v_lshlrev_b32_e32 v140, 16, v155
	v_and_b32_e32 v141, 0xffff0000, v155
	v_pk_mul_f32 v[138:139], v[60:61], v[138:139]
	v_pk_mul_f32 v[140:141], v[62:63], v[140:141]
	v_pk_fma_f32 v[12:13], v[12:13], s[34:35], v[138:139] op_sel_hi:[1,0,1]
	v_pk_fma_f32 v[14:15], v[14:15], s[34:35], v[140:141] op_sel_hi:[1,0,1]
	v_add_f32_e32 v138, v12, v13
	v_add_f32_e32 v139, v14, v15
	v_add_f32_e32 v138, v138, v139
	v_add_f32_e32 v138, v138, v142
	s_nop 1
	s_ashr_i32 s9, s8, 31
	s_add_i32 s16, s16, 1
	s_waitcnt lgkmcnt(0)
	v_add_f32_dpp v138, v138, v138 quad_perm:[1,0,3,2] row_mask:0xf bank_mask:0xf
	s_nop 1
	s_waitcnt lgkmcnt(0)
	v_add_f32_dpp v138, v138, v138 quad_perm:[2,3,0,1] row_mask:0xf bank_mask:0xf
	s_nop 1
	s_waitcnt lgkmcnt(0)
	v_add_f32_dpp v138, v138, v138 row_half_mirror row_mask:0xf bank_mask:0xf
	s_nop 1
	s_waitcnt lgkmcnt(0)
	v_add_f32_dpp v138, v138, v138 row_mirror row_mask:0xf bank_mask:0xf
	v_mov_b32_e32 v139, v138
	s_nop 1
	v_permlane16_swap_b32_e32 v139, v138
	s_waitcnt lgkmcnt(0)
	v_add_f32_e32 v138, v138, v139
	v_mov_b32_e32 v139, v138
	s_nop 1
	v_permlane32_swap_b32_e32 v139, v138
	s_waitcnt lgkmcnt(0)
	v_add_f32_e32 v148, v138, v139
	v_fmamk_f32 v89, v148, 0xba800000, v89
	v_fmac_f32_e32 v88, 0xba800000, v148
	v_fmamk_f32 v91, v148, 0xba800000, v91
	v_fmac_f32_e32 v90, 0xba800000, v148
	v_pk_mul_f32 v[138:139], v[90:91], v[90:91]
	v_pk_mul_f32 v[140:141], v[88:89], v[88:89]
	v_fmamk_f32 v85, v148, 0xba800000, v85
	v_pk_mov_b32 v[142:143], v[140:141], v[138:139] op_sel:[1,0]
	v_mov_b32_e32 v141, v139
	v_pk_add_f32 v[138:139], v[142:143], v[140:141]
	v_fmac_f32_e32 v84, 0xba800000, v148
	v_fmamk_f32 v87, v148, 0xba800000, v87
	v_fmac_f32_e32 v86, 0xba800000, v148
	v_pk_add_f32 v[138:139], v[138:139], v[138:139] op_sel_hi:[0,1]
	v_pk_mul_f32 v[140:141], v[86:87], v[86:87]
	v_pk_mul_f32 v[142:143], v[84:85], v[84:85]
	v_fmac_f32_e32 v80, 0xba800000, v148
	v_pk_mov_b32 v[146:147], v[142:143], v[140:141] op_sel:[1,0]
	v_mov_b32_e32 v143, v141
	v_fmamk_f32 v81, v148, 0xba800000, v81
	v_fmac_f32_e32 v82, 0xba800000, v148
	v_mul_f32_e32 v138, v80, v80
	v_pk_add_f32 v[140:141], v[146:147], v[142:143]
	v_fmamk_f32 v83, v148, 0xba800000, v83
	v_pk_fma_f32 v[142:143], v[80:81], v[80:81], v[138:139] op_sel_hi:[1,1,0]
	v_mul_f32_e32 v138, v82, v82
	v_pk_add_f32 v[140:141], v[140:141], v[140:141] op_sel_hi:[0,1]
	v_pk_fma_f32 v[146:147], v[82:83], v[82:83], v[138:139] op_sel_hi:[1,1,0]
	v_fmamk_f32 v15, v148, 0xba800000, v15
	v_fmac_f32_e32 v14, 0xba800000, v148
	v_fmamk_f32 v13, v148, 0xba800000, v13
	v_fmac_f32_e32 v12, 0xba800000, v148
	v_mul_f32_e32 v142, v12, v12
	v_mul_f32_e32 v146, v13, v13
	v_mul_f32_e32 v138, v14, v14
	v_mul_f32_e32 v140, v15, v15
	v_pk_add_f32 v[142:143], v[142:143], v[146:147]
	v_pk_add_f32 v[138:139], v[138:139], v[140:141]
	s_nop 0
	v_pk_add_f32 v[138:139], v[142:143], v[138:139]
	s_nop 0
	v_add_f32_e32 v138, v138, v139
	s_nop 1
	s_waitcnt lgkmcnt(0)
; template <int MODE, bool ROUTE, int H8> ...
;     ...
;             const float mean = wave_sum(s) * (1.f / D); float s2 = 0.f;
; #pragma unroll
;             for (int jj = 0; jj < 4; ++jj) { v[jj] = v[jj] - mean; s2 += (v[jj][0] * v[jj][0] + v[jj][1] * v[jj][1]) + (v[jj][2] * v[jj][2] + v[jj][3] * v[jj][3]); }
;             const float rstd = 1.0f / sqrtf(wave_sum(s2) * (1.f / D) + LN_EPS);
;             float* orow = F.out + (size_t)row * D + 4 * F.lane;
;             unsigned long long* h8 = (unsigned long long*)(HB + (size_t)row * D + 4 * F.lane);
;             float lg[NE];
; #pragma unroll
;             for (int e = 0; e < NE; ++e) lg[e] = 0.f;
;             f32x4 hv[4];
; #pragma unroll
;             for (int jj = 0; jj < 4; ++jj) {
;                 const f32x4 xn = v[jj] * rstd * g4[jj] + b4[jj];
;                 if (xout16) __builtin_nontemporal_store(__builtin_bit_cast(u32x2, __builtin_convertvector(xn, f16x4_t)), (u32x2*)(XH + (size_t)row * D + 4 * F.lane + 256 * jj));
;                 else __builtin_nontemporal_store(xn, (f32x4*)(orow + 256 * jj));
;                 if (next_mod) {
;                     const f32x4 h = xn * (1.0f + nsc[jj]) + nsh[jj];
;                     hv[jj] = h;
;                     if (H8 == 0) h8[64 * jj] = (unsigned long long)pk2(h[0], h[1]) | ((unsigned long long)pk2(h[2], h[3]) << 32);
;                     if (ROUTE) {
; #pragma unroll
;                         for (int i = 0; i < 4; ++i) { const LAS f32x4* wp = (const LAS f32x4*)(wr_l + (4 * F.lane + 256 * jj + i) * 8); const f32x4 wa = wp[0], wb = wp[1];
;                             lg[0] += h[i] * wa[0]; lg[1] += h[i] * wa[1]; lg[2] += h[i] * wa[2]; lg[3] += h[i] * wa[3]; lg[4] += h[i] * wb[0]; lg[5] += h[i] * wb[1]; lg[6] += h[i] * wb[2]; lg[7] += h[i] * wb[3]; }
;                     }
;                 }
;             }
;             if (H8 == 2 && next_mod) {
;                 float am = 0.f;
; #pragma unroll
;                 for (int jj = 0; jj < 4; ++jj) am = fmaxf(fmaxf(am, fmaxf(fabsf(hv[jj][0]), fabsf(hv[jj][1]))), fmaxf(fabsf(hv[jj][2]), fabsf(hv[jj][3])));
;                 h_store_i8(hv, am, (signed char*)HB + (size_t)row * D + 4 * F.lane, (float*)(F.ws + WS_HSC) + row, F.lane);
;             }
;             if (H8 == 1 && next_mod) {
;                 unsigned* q8 = (unsigned*)((signed char*)HB + (size_t)row * D + 4 * F.lane);
; #pragma unroll
	v_add_f32_dpp v138, v138, v138 quad_perm:[1,0,3,2] row_mask:0xf bank_mask:0xf
	s_nop 1
	s_waitcnt lgkmcnt(0)
	v_add_f32_dpp v138, v138, v138 quad_perm:[2,3,0,1] row_mask:0xf bank_mask:0xf
	s_nop 1
	s_waitcnt lgkmcnt(0)
	v_add_f32_dpp v138, v138, v138 row_half_mirror row_mask:0xf bank_mask:0xf
	s_nop 1
	s_waitcnt lgkmcnt(0)
	v_add_f32_dpp v138, v138, v138 row_mirror row_mask:0xf bank_mask:0xf
	v_mov_b32_e32 v139, v138
	s_nop 1
	v_permlane16_swap_b32_e32 v139, v138
	s_waitcnt lgkmcnt(0)
	v_add_f32_e32 v138, v138, v139
	v_mov_b32_e32 v139, v138
	s_nop 1
	v_permlane32_swap_b32_e32 v139, v138
	s_waitcnt lgkmcnt(0)
	v_add_f32_e32 v138, v138, v139
	v_fmamk_f32 v138, v138, 0x3a800000, v221
	v_mul_f32_e32 v139, 0x4f800000, v138
	v_cmp_gt_f32_e32 vcc, s85, v138
	s_nop 1
	v_cndmask_b32_e32 v138, v138, v139, vcc
	v_sqrt_f32_e32 v139, v138
	s_nop 0
	v_add_u32_e32 v140, -1, v139
	v_fma_f32 v141, -v140, v139, v138
	v_cmp_ge_f32_e64 s[2:3], 0, v141
	v_add_u32_e32 v141, 1, v139
	s_nop 0
	v_cndmask_b32_e64 v140, v139, v140, s[2:3]
	v_fma_f32 v139, -v141, v139, v138
	v_cmp_lt_f32_e64 s[2:3], 0, v139
	s_nop 1
	v_cndmask_b32_e64 v139, v140, v141, s[2:3]
	v_mul_f32_e32 v140, 0x37800000, v139
	v_cndmask_b32_e32 v139, v139, v140, vcc
	v_cmp_class_f32_e32 vcc, v138, v220
	s_nop 1
	v_cndmask_b32_e32 v138, v139, v138, vcc
	v_div_scale_f32 v139, s[2:3], v138, v138, 1.0
	v_rcp_f32_e32 v140, v139
	s_lshl_b64 s[2:3], s[8:9], 10
	s_lshl_b64 s[8:9], s[8:9], 11
	s_cmp_eq_u32 s16, 32
	v_fma_f32 v141, -v139, v140, 1.0
	v_fmac_f32_e32 v140, v141, v140
	v_div_scale_f32 v141, vcc, 1.0, v138, 1.0
	v_mul_f32_e32 v142, v141, v140
	v_fma_f32 v143, -v139, v142, v141
	v_fmac_f32_e32 v142, v143, v140
	v_fma_f32 v139, -v139, v142, v141
	v_div_fmas_f32 v139, v139, v140, v142
	v_div_fixup_f32 v138, v139, v138, 1.0
	v_pk_mul_f32 v[90:91], v[90:91], v[138:139] op_sel_hi:[1,0]
	v_pk_mul_f32 v[88:89], v[88:89], v[138:139] op_sel_hi:[1,0]
	v_pk_fma_f32 v[90:91], v[4:5], v[90:91], v[18:19]
	v_pk_fma_f32 v[88:89], v[2:3], v[88:89], v[16:17]
	v_pk_mul_f32 v[84:85], v[84:85], v[138:139] op_sel_hi:[1,0]
	v_pk_mul_f32 v[14:15], v[14:15], v[138:139] op_sel_hi:[1,0]
	v_pk_mul_f32 v[12:13], v[12:13], v[138:139] op_sel_hi:[1,0]
	v_cvt_pk_f16_f32 v141, v90, v91
	v_cvt_pk_f16_f32 v140, v88, v89
	v_lshl_add_u64 v[142:143], v[104:105], 0, s[8:9]
	v_pk_fma_f32 v[88:89], v[10:11], v[88:89], v[44:45]
	v_pk_fma_f32 v[84:85], v[6:7], v[84:85], v[20:21]
	v_pk_fma_f32 v[12:13], v[28:29], v[12:13], v[36:37]
	v_pk_fma_f32 v[14:15], v[30:31], v[14:15], v[38:39]
	global_store_dwordx2 v[142:143], v[140:141], off nt
	v_pk_mul_f32 v[86:87], v[86:87], v[138:139] op_sel_hi:[1,0]
	v_cvt_pk_f16_f32 v140, v84, v85
	v_pk_fma_f32 v[84:85], v[122:123], v[84:85], v[48:49]
	v_pk_mul_f32 v[82:83], v[82:83], v[138:139] op_sel_hi:[1,0]
	v_pk_mul_f32 v[80:81], v[80:81], v[138:139] op_sel_hi:[1,0]
	v_cvt_pk_f16_f32 v139, v14, v15
	v_cvt_pk_f16_f32 v138, v12, v13
	v_mul_f32_e32 v88, 0x41000000, v88
	v_mul_f32_e32 v89, 0x41000000, v89
	v_pk_fma_f32 v[90:91], v[118:119], v[90:91], v[46:47]
	global_store_dwordx2 v[142:143], v[138:139], off offset:1536 nt
	v_med3_f32 v88, v88, s80, v227
	v_med3_f32 v89, v89, s80, v227
	v_mov_b32_e32 v138, v67
	v_mul_f32_e32 v84, 0x41000000, v84
	v_mul_f32_e32 v85, 0x41000000, v85
	v_cvt_pk_fp8_f32 v138, v88, v89
	v_mul_f32_e32 v88, 0x41000000, v90
	v_med3_f32 v84, v84, s80, v227
	v_med3_f32 v85, v85, s80, v227
	v_mov_b32_e32 v90, v67
	v_pk_fma_f32 v[86:87], v[8:9], v[86:87], v[22:23]
	v_cvt_pk_fp8_f32 v90, v84, v85
	v_cvt_pk_f16_f32 v141, v86, v87
	v_pk_fma_f32 v[86:87], v[120:121], v[86:87], v[50:51]
	v_pk_fma_f32 v[80:81], v[24:25], v[80:81], v[32:33]
	global_store_dwordx2 v[142:143], v[140:141], off offset:512 nt
	v_cvt_pk_f16_f32 v140, v80, v81
	v_pk_fma_f32 v[80:81], v[126:127], v[80:81], v[68:69]
	v_mul_f32_e32 v84, 0x41000000, v86
	v_mul_f32_e32 v85, 0x41000000, v87
	v_med3_f32 v84, v84, s80, v227
	v_med3_f32 v85, v85, s80, v227
	v_mul_f32_e32 v80, 0x41000000, v80
	v_mul_f32_e32 v81, 0x41000000, v81
	v_cvt_pk_fp8_f32 v90, v84, v85 op_sel:[0,0,1]
	v_med3_f32 v80, v80, s80, v227
	v_med3_f32 v81, v81, s80, v227
	v_mov_b32_e32 v84, v67
	v_pk_fma_f32 v[82:83], v[26:27], v[82:83], v[34:35]
	v_cvt_pk_fp8_f32 v84, v80, v81
	v_cvt_pk_f16_f32 v141, v82, v83
	v_pk_fma_f32 v[82:83], v[124:125], v[82:83], v[70:71]
	v_pk_fma_f32 v[12:13], v[130:131], v[12:13], v[72:73]
	v_mul_f32_e32 v80, 0x41000000, v82
	v_mul_f32_e32 v81, 0x41000000, v83
	v_med3_f32 v80, v80, s80, v227
	v_med3_f32 v81, v81, s80, v227
	v_mul_f32_e32 v12, 0x41000000, v12
	v_mul_f32_e32 v13, 0x41000000, v13
	v_cvt_pk_fp8_f32 v84, v80, v81 op_sel:[0,0,1]
	v_med3_f32 v12, v12, s80, v227
	v_med3_f32 v13, v13, s80, v227
	v_mov_b32_e32 v80, v67
	v_cvt_pk_fp8_f32 v80, v12, v13
	v_pk_fma_f32 v[14:15], v[128:129], v[14:15], v[74:75]
	v_mul_f32_e32 v89, 0x41000000, v91
	v_mul_f32_e32 v12, 0x41000000, v14
	v_mul_f32_e32 v13, 0x41000000, v15
	v_med3_f32 v88, v88, s80, v227
	v_med3_f32 v89, v89, s80, v227
	v_med3_f32 v12, v12, s80, v227
	v_med3_f32 v13, v13, s80, v227
	v_cvt_pk_fp8_f32 v138, v88, v89 op_sel:[0,0,1]
	v_cvt_pk_fp8_f32 v80, v12, v13 op_sel:[0,0,1]
	v_lshl_add_u64 v[88:89], v[108:109], 0, s[2:3]
	global_store_dwordx2 v[142:143], v[140:141], off offset:1024 nt
	global_store_dword v[88:89], v138, off
	global_store_dword v[88:89], v90, off offset:256
	global_store_dword v[88:89], v84, off offset:512
	global_store_dword v[88:89], v80, off offset:768
	s_cbranch_scc1 .LBB0_832
	s_waitcnt vmcnt(9)
	v_mov_b64_e32 v[148:149], v[116:117]
	v_mov_b64_e32 v[142:143], v[114:115]
	v_mov_b64_e32 v[140:141], v[112:113]
	v_mov_b64_e32 v[138:139], v[110:111]
	s_waitcnt vmcnt(8)
	v_mov_b64_e32 v[154:155], v[144:145]
	v_mov_b64_e32 v[152:153], v[136:137]
	v_mov_b64_e32 v[150:151], v[134:135]
	v_mov_b64_e32 v[146:147], v[132:133]
	v_mov_b32_e32 v88, v92
	v_mov_b32_e32 v89, v93
	v_mov_b32_e32 v90, v94
	v_mov_b32_e32 v91, v95
	v_mov_b32_e32 v84, v96
	v_mov_b32_e32 v85, v97
	v_mov_b32_e32 v86, v98
	v_mov_b32_e32 v87, v99
	v_mov_b32_e32 v80, v100
	v_mov_b32_e32 v81, v101
	v_mov_b32_e32 v82, v102
	v_mov_b32_e32 v83, v103
	v_mov_b32_e32 v12, v76
	v_mov_b32_e32 v13, v77
	v_mov_b32_e32 v14, v78
	v_mov_b32_e32 v15, v79
	s_branch .LBB0_850

; template <int MODE, bool ROUTE, int H8> ...
;     ...
;             if (MODE == 1) { w0 = __builtin_bit_cast(float, wq0); w1 = __builtin_bit_cast(float, wq1); }
; #pragma unroll
;             for (int jj = 0; jj < 4; ++jj) {
;                 f32x4 x = xq[jj];
;                 if (xin16) x = __builtin_convertvector(__builtin_bit_cast(f16x4_t, xhq[jj]), f32x4);
;                 f32x4 y;
;                 if (MODE == 0) { const u32x2 yw = yq0[jj]; y = (f32x4){bflo(yw.x), bfhi(yw.x), bflo(yw.y), bfhi(yw.y)}; }
;                 else { const u32x2 ya = yq0[jj], yb = yq1[jj];
;                     y = (f32x4){bflo(ya.x), bfhi(ya.x), bflo(ya.y), bfhi(ya.y)} * w0 + (f32x4){bflo(yb.x), bfhi(yb.x), bflo(yb.y), bfhi(yb.y)} * w1; }
;                 v[jj] = x * ALPHA + gt[jj] * y;
;                 s += (v[jj][0] + v[jj][1]) + (v[jj][2] + v[jj][3]);
;             }
;             if (r + 1 < 32) LN_LOAD(r + 1);
;             const float mean = wave_sum(s) * (1.f / D); float s2 = 0.f;
.LBB0_1242:
	v_cvt_f32_f16_sdwa v169, v152 dst_sel:DWORD dst_unused:UNUSED_PAD src0_sel:WORD_1
	v_cvt_f32_f16_sdwa v171, v153 dst_sel:DWORD dst_unused:UNUSED_PAD src0_sel:WORD_1
	v_cvt_f32_f16_e32 v168, v152
	v_cvt_f32_f16_e32 v170, v153
	v_lshlrev_b32_e32 v172, 16, v160
	v_and_b32_e32 v173, 0xffff0000, v160
	v_lshlrev_b32_e32 v160, 16, v161
	v_and_b32_e32 v161, 0xffff0000, v161
	v_lshlrev_b32_e32 v152, 16, v154
	v_and_b32_e32 v153, 0xffff0000, v154
	v_lshlrev_b32_e32 v154, 16, v155
	v_and_b32_e32 v155, 0xffff0000, v155
	v_pk_mul_f32 v[172:173], v[98:99], v[172:173] op_sel:[1,0]
	v_pk_mul_f32 v[160:161], v[98:99], v[160:161] op_sel:[1,0]
	v_pk_fma_f32 v[152:153], v[98:99], v[152:153], v[172:173] op_sel_hi:[0,1,1]
	v_pk_fma_f32 v[154:155], v[98:99], v[154:155], v[160:161] op_sel_hi:[0,1,1]
	v_pk_mul_f32 v[160:161], v[50:51], v[152:153]
	v_pk_mul_f32 v[152:153], v[52:53], v[154:155]
	v_pk_fma_f32 v[154:155], v[168:169], s[34:35], v[160:161] op_sel_hi:[1,0,1]
	v_pk_fma_f32 v[152:153], v[170:171], s[34:35], v[152:153] op_sel_hi:[1,0,1]
	v_cvt_f32_f16_sdwa v161, v88 dst_sel:DWORD dst_unused:UNUSED_PAD src0_sel:WORD_1
	v_cvt_f32_f16_sdwa v169, v89 dst_sel:DWORD dst_unused:UNUSED_PAD src0_sel:WORD_1
	v_cvt_f32_f16_e32 v160, v88
	v_cvt_f32_f16_e32 v168, v89
	v_lshlrev_b32_e32 v170, 16, v158
	v_and_b32_e32 v171, 0xffff0000, v158
	v_lshlrev_b32_e32 v158, 16, v159
	v_and_b32_e32 v159, 0xffff0000, v159
	v_lshlrev_b32_e32 v88, 16, v90
	v_and_b32_e32 v89, 0xffff0000, v90
	v_lshlrev_b32_e32 v90, 16, v91
	v_and_b32_e32 v91, 0xffff0000, v91
	v_pk_mul_f32 v[170:171], v[98:99], v[170:171] op_sel:[1,0]
	v_pk_mul_f32 v[158:159], v[98:99], v[158:159] op_sel:[1,0]
	v_pk_fma_f32 v[88:89], v[98:99], v[88:89], v[170:171] op_sel_hi:[0,1,1]
	v_pk_fma_f32 v[90:91], v[98:99], v[90:91], v[158:159] op_sel_hi:[0,1,1]
	v_pk_mul_f32 v[158:159], v[62:63], v[88:89]
	v_pk_mul_f32 v[88:89], v[64:65], v[90:91]
	v_add_f32_e32 v66, v154, v155
	v_add_f32_e32 v101, v152, v153
	v_pk_fma_f32 v[88:89], v[168:169], s[34:35], v[88:89] op_sel_hi:[1,0,1]
	v_pk_fma_f32 v[90:91], v[160:161], s[34:35], v[158:159] op_sel_hi:[1,0,1]
	v_add_f32_e32 v66, v66, v101
	v_add_f32_e32 v101, v90, v91
	v_add_f32_e32 v158, v88, v89
	v_add_f32_e32 v101, v101, v158
	v_cvt_f32_f16_sdwa v159, v92 dst_sel:DWORD dst_unused:UNUSED_PAD src0_sel:WORD_1
	v_cvt_f32_f16_sdwa v161, v93 dst_sel:DWORD dst_unused:UNUSED_PAD src0_sel:WORD_1
	v_cvt_f32_f16_e32 v158, v92
	v_cvt_f32_f16_e32 v160, v93
	v_lshlrev_b32_e32 v168, 16, v156
	v_and_b32_e32 v169, 0xffff0000, v156
	v_lshlrev_b32_e32 v156, 16, v157
	v_and_b32_e32 v157, 0xffff0000, v157
	v_lshlrev_b32_e32 v92, 16, v94
	v_and_b32_e32 v93, 0xffff0000, v94
	v_lshlrev_b32_e32 v94, 16, v95
	v_and_b32_e32 v95, 0xffff0000, v95
	v_pk_mul_f32 v[168:169], v[98:99], v[168:169] op_sel:[1,0]
	v_pk_mul_f32 v[156:157], v[98:99], v[156:157] op_sel:[1,0]
	v_pk_fma_f32 v[92:93], v[98:99], v[92:93], v[168:169] op_sel_hi:[0,1,1]
	v_pk_fma_f32 v[94:95], v[98:99], v[94:95], v[156:157] op_sel_hi:[0,1,1]
	v_pk_mul_f32 v[156:157], v[68:69], v[92:93]
	v_pk_mul_f32 v[92:93], v[70:71], v[94:95]
	v_add_f32_e32 v66, 0, v66
	v_pk_fma_f32 v[92:93], v[160:161], s[34:35], v[92:93] op_sel_hi:[1,0,1]
	v_pk_fma_f32 v[94:95], v[158:159], s[34:35], v[156:157] op_sel_hi:[1,0,1]
	v_add_f32_e32 v66, v101, v66
	v_add_f32_e32 v101, v94, v95
	v_add_f32_e32 v156, v92, v93
	v_add_f32_e32 v101, v101, v156
	v_cvt_f32_f16_sdwa v157, v84 dst_sel:DWORD dst_unused:UNUSED_PAD src0_sel:WORD_1
	v_cvt_f32_f16_sdwa v159, v85 dst_sel:DWORD dst_unused:UNUSED_PAD src0_sel:WORD_1
	v_cvt_f32_f16_e32 v156, v84
	v_cvt_f32_f16_e32 v158, v85
	v_lshlrev_b32_e32 v160, 16, v96
	v_and_b32_e32 v161, 0xffff0000, v96
	v_lshlrev_b32_e32 v96, 16, v97
	v_and_b32_e32 v97, 0xffff0000, v97
	v_lshlrev_b32_e32 v84, 16, v86
	v_and_b32_e32 v85, 0xffff0000, v86
	v_lshlrev_b32_e32 v86, 16, v87
	v_and_b32_e32 v87, 0xffff0000, v87
	v_pk_mul_f32 v[160:161], v[98:99], v[160:161] op_sel:[1,0]
	v_pk_mul_f32 v[96:97], v[98:99], v[96:97] op_sel:[1,0]
	v_pk_fma_f32 v[84:85], v[98:99], v[84:85], v[160:161] op_sel_hi:[0,1,1]
	v_pk_fma_f32 v[86:87], v[98:99], v[86:87], v[96:97] op_sel_hi:[0,1,1]
	v_pk_mul_f32 v[84:85], v[80:81], v[84:85]
	v_pk_mul_f32 v[86:87], v[82:83], v[86:87]
	v_pk_fma_f32 v[98:99], v[156:157], s[34:35], v[84:85] op_sel_hi:[1,0,1]
	v_pk_fma_f32 v[96:97], v[158:159], s[34:35], v[86:87] op_sel_hi:[1,0,1]
	v_add_f32_e32 v84, v98, v99
	v_add_f32_e32 v85, v96, v97
	v_add_f32_e32 v66, v101, v66
	v_add_f32_e32 v84, v84, v85
	v_add_f32_e32 v66, v84, v66
	s_nop 1
	s_ashr_i32 s47, s46, 31
	s_waitcnt lgkmcnt(0)
; template <int MODE, bool ROUTE, int H8> ...
;     ...
;             const float mean = wave_sum(s) * (1.f / D); float s2 = 0.f;
; #pragma unroll
;             for (int jj = 0; jj < 4; ++jj) { v[jj] = v[jj] - mean; s2 += (v[jj][0] * v[jj][0] + v[jj][1] * v[jj][1]) + (v[jj][2] * v[jj][2] + v[jj][3] * v[jj][3]); }
;             const float rstd = 1.0f / sqrtf(wave_sum(s2) * (1.f / D) + LN_EPS);
;             float* orow = F.out + (size_t)row * D + 4 * F.lane;
;             unsigned long long* h8 = (unsigned long long*)(HB + (size_t)row * D + 4 * F.lane);
;             float lg[NE];
; #pragma unroll
;             for (int e = 0; e < NE; ++e) lg[e] = 0.f;
;             f32x4 hv[4];
; #pragma unroll
;             for (int jj = 0; jj < 4; ++jj) {
;                 const f32x4 xn = v[jj] * rstd * g4[jj] + b4[jj];
;                 if (xout16) __builtin_nontemporal_store(__builtin_bit_cast(u32x2, __builtin_convertvector(xn, f16x4_t)), (u32x2*)(XH + (size_t)row * D + 4 * F.lane + 256 * jj));
;                 else __builtin_nontemporal_store(xn, (f32x4*)(orow + 256 * jj));
	v_add_f32_dpp v66, v66, v66 quad_perm:[1,0,3,2] row_mask:0xf bank_mask:0xf
	s_nop 1
	s_waitcnt lgkmcnt(0)
	v_add_f32_dpp v66, v66, v66 quad_perm:[2,3,0,1] row_mask:0xf bank_mask:0xf
	s_nop 1
	s_waitcnt lgkmcnt(0)
	v_add_f32_dpp v66, v66, v66 row_half_mirror row_mask:0xf bank_mask:0xf
	s_nop 1
	s_waitcnt lgkmcnt(0)
	v_add_f32_dpp v66, v66, v66 row_mirror row_mask:0xf bank_mask:0xf
	v_mov_b32_e32 v84, v66
	s_nop 1
	v_permlane16_swap_b32_e32 v84, v66
	s_waitcnt lgkmcnt(0)
	v_add_f32_e32 v66, v66, v84
	v_mov_b32_e32 v84, v66
	s_nop 1
	v_permlane32_swap_b32_e32 v84, v66
	s_waitcnt lgkmcnt(0)
	v_add_f32_e32 v101, v66, v84
	v_fmamk_f32 v155, v101, 0xba800000, v155
	v_fmac_f32_e32 v154, 0xba800000, v101
	v_fmamk_f32 v153, v101, 0xba800000, v153
	v_fmac_f32_e32 v152, 0xba800000, v101
	v_pk_mul_f32 v[84:85], v[152:153], v[152:153]
	v_pk_mul_f32 v[86:87], v[154:155], v[154:155]
	v_fmamk_f32 v89, v101, 0xba800000, v89
	v_pk_mov_b32 v[156:157], v[86:87], v[84:85] op_sel:[1,0]
	v_mov_b32_e32 v87, v85
	v_fmac_f32_e32 v88, 0xba800000, v101
	v_fmamk_f32 v91, v101, 0xba800000, v91
	v_fmac_f32_e32 v90, 0xba800000, v101
	v_pk_add_f32 v[84:85], v[156:157], v[86:87]
	v_pk_mul_f32 v[86:87], v[88:89], v[88:89]
	v_pk_mul_f32 v[156:157], v[90:91], v[90:91]
	v_fmac_f32_e32 v94, 0xba800000, v101
	v_pk_mov_b32 v[158:159], v[156:157], v[86:87] op_sel:[1,0]
	v_mov_b32_e32 v157, v87
	v_fmac_f32_e32 v92, 0xba800000, v101
	v_fmamk_f32 v95, v101, 0xba800000, v95
	v_mul_f32_e32 v66, v94, v94
	v_pk_add_f32 v[86:87], v[158:159], v[156:157]
	v_fmamk_f32 v93, v101, 0xba800000, v93
	v_pk_fma_f32 v[156:157], v[94:95], v[94:95], v[66:67] op_sel_hi:[1,1,0]
	v_mul_f32_e32 v66, v92, v92
	v_pk_add_f32 v[84:85], v[84:85], v[84:85] op_sel_hi:[0,1]
	v_pk_add_f32 v[86:87], v[86:87], v[86:87] op_sel_hi:[0,1]
	v_pk_fma_f32 v[158:159], v[92:93], v[92:93], v[66:67] op_sel_hi:[1,1,0]
	v_fmamk_f32 v97, v101, 0xba800000, v97
	v_fmac_f32_e32 v96, 0xba800000, v101
	v_fmamk_f32 v99, v101, 0xba800000, v99
	v_fmac_f32_e32 v98, 0xba800000, v101
	v_mul_f32_e32 v156, v98, v98
	v_mul_f32_e32 v158, v99, v99
	v_mul_f32_e32 v84, v96, v96
	v_mul_f32_e32 v86, v97, v97
	v_pk_add_f32 v[156:157], v[156:157], v[158:159]
	v_pk_add_f32 v[84:85], v[84:85], v[86:87]
	s_nop 0
	v_pk_add_f32 v[84:85], v[156:157], v[84:85]
	s_nop 0
	v_add_f32_e32 v66, v84, v85
	s_nop 1
	s_waitcnt lgkmcnt(0)
	v_add_f32_dpp v66, v66, v66 quad_perm:[1,0,3,2] row_mask:0xf bank_mask:0xf
	s_nop 1
	s_waitcnt lgkmcnt(0)
	v_add_f32_dpp v66, v66, v66 quad_perm:[2,3,0,1] row_mask:0xf bank_mask:0xf
	s_nop 1
	s_waitcnt lgkmcnt(0)
	v_add_f32_dpp v66, v66, v66 row_half_mirror row_mask:0xf bank_mask:0xf
	s_nop 1
	s_waitcnt lgkmcnt(0)
	v_add_f32_dpp v66, v66, v66 row_mirror row_mask:0xf bank_mask:0xf
	v_mov_b32_e32 v84, v66
	s_nop 1
	v_permlane16_swap_b32_e32 v84, v66
	s_waitcnt lgkmcnt(0)
	v_add_f32_e32 v66, v66, v84
	v_mov_b32_e32 v84, v66
	s_nop 1
	v_permlane32_swap_b32_e32 v84, v66
	s_waitcnt lgkmcnt(0)
	v_add_f32_e32 v66, v66, v84
	v_fmamk_f32 v66, v66, 0x3a800000, v221
	v_mul_f32_e32 v84, 0x4f800000, v66
	v_cmp_gt_f32_e32 vcc, s85, v66
	s_nop 1
	v_cndmask_b32_e32 v66, v66, v84, vcc
	v_sqrt_f32_e32 v84, v66
	s_nop 0
	v_add_u32_e32 v85, -1, v84
	v_fma_f32 v86, -v85, v84, v66
	v_cmp_ge_f32_e64 s[42:43], 0, v86
	v_add_u32_e32 v86, 1, v84
	s_nop 0
	v_cndmask_b32_e64 v85, v84, v85, s[42:43]
	v_fma_f32 v84, -v86, v84, v66
	v_cmp_lt_f32_e64 s[42:43], 0, v84
	s_nop 1
	v_cndmask_b32_e64 v84, v85, v86, s[42:43]
	v_mul_f32_e32 v85, 0x37800000, v84
	v_cndmask_b32_e32 v84, v84, v85, vcc
	v_cmp_class_f32_e32 vcc, v66, v220
	s_nop 1
	v_cndmask_b32_e32 v66, v84, v66, vcc
	v_div_scale_f32 v84, s[24:25], v66, v66, 1.0
	v_rcp_f32_e32 v85, v84
	s_lshl_b64 s[24:25], s[46:47], 11
	s_add_u32 s42, s12, s24
	s_addc_u32 s43, s13, s25
	v_fma_f32 v86, -v84, v85, 1.0
	v_fmac_f32_e32 v85, v86, v85
	v_div_scale_f32 v86, vcc, 1.0, v66, 1.0
	v_mul_f32_e32 v87, v86, v85
	v_fma_f32 v101, -v84, v87, v86
	v_fmac_f32_e32 v87, v101, v85
	v_fma_f32 v84, -v84, v87, v86
	v_div_fmas_f32 v84, v84, v85, v87
	v_div_fixup_f32 v156, v84, v66, 1.0
	v_pk_mul_f32 v[84:85], v[154:155], v[156:157] op_sel_hi:[1,0]
	v_pk_mul_f32 v[86:87], v[152:153], v[156:157] op_sel_hi:[1,0]
	v_pk_fma_f32 v[84:85], v[18:19], v[84:85], v[26:27]
	v_pk_fma_f32 v[86:87], v[20:21], v[86:87], v[28:29]
	s_mov_b64 s[24:25], -1
	s_and_b64 vcc, exec, s[0:1]
	v_lshlrev_b32_e32 v66, 1, v100
	s_cbranch_vccz .LBB0_1244
	v_cvt_pk_f16_f32 v153, v86, v87
	v_cvt_pk_f16_f32 v152, v84, v85
	s_mov_b64 s[24:25], 0
	global_store_dwordx2 v66, v[152:153], s[42:43] nt

; template <int MODE, bool ROUTE, int H8> ...
;     ...
;             for (int jj = 0; jj < 4; ++jj) {
;                 f32x4 x = xq[jj];
;                 if (xin16) x = __builtin_convertvector(__builtin_bit_cast(f16x4_t, xhq[jj]), f32x4);
;                 f32x4 y;
;                 if (MODE == 0) { const u32x2 yw = yq0[jj]; y = (f32x4){bflo(yw.x), bfhi(yw.x), bflo(yw.y), bfhi(yw.y)}; }
;                 else { const u32x2 ya = yq0[jj], yb = yq1[jj];
;                     y = (f32x4){bflo(ya.x), bfhi(ya.x), bflo(ya.y), bfhi(ya.y)} * w0 + (f32x4){bflo(yb.x), bfhi(yb.x), bflo(yb.y), bfhi(yb.y)} * w1; }
;                 v[jj] = x * ALPHA + gt[jj] * y;
;                 s += (v[jj][0] + v[jj][1]) + (v[jj][2] + v[jj][3]);
;             }
;             if (r + 1 < 32) LN_LOAD(r + 1);
;             const float mean = wave_sum(s) * (1.f / D); float s2 = 0.f;
.LBB0_1280:
	v_cvt_f32_f16_sdwa v143, v96 dst_sel:DWORD dst_unused:UNUSED_PAD src0_sel:WORD_1
	v_cvt_f32_f16_sdwa v145, v97 dst_sel:DWORD dst_unused:UNUSED_PAD src0_sel:WORD_1
	v_cvt_f32_f16_e32 v142, v96
	v_cvt_f32_f16_e32 v144, v97
	v_lshlrev_b32_e32 v96, 16, v98
	v_and_b32_e32 v97, 0xffff0000, v98
	v_lshlrev_b32_e32 v98, 16, v99
	v_and_b32_e32 v99, 0xffff0000, v99
	v_pk_mul_f32 v[96:97], v[50:51], v[96:97]
	v_pk_mul_f32 v[98:99], v[52:53], v[98:99]
	v_pk_fma_f32 v[152:153], v[142:143], s[34:35], v[96:97] op_sel_hi:[1,0,1]
	v_pk_fma_f32 v[144:145], v[144:145], s[34:35], v[98:99] op_sel_hi:[1,0,1]
	v_add_f32_e32 v66, v152, v153
	v_add_f32_e32 v96, v144, v145
	v_add_f32_e32 v66, v66, v96
	v_cvt_f32_f16_sdwa v97, v88 dst_sel:DWORD dst_unused:UNUSED_PAD src0_sel:WORD_1
	v_cvt_f32_f16_sdwa v99, v89 dst_sel:DWORD dst_unused:UNUSED_PAD src0_sel:WORD_1
	v_cvt_f32_f16_e32 v96, v88
	v_cvt_f32_f16_e32 v98, v89
	v_lshlrev_b32_e32 v88, 16, v90
	v_and_b32_e32 v89, 0xffff0000, v90
	v_lshlrev_b32_e32 v90, 16, v91
	v_and_b32_e32 v91, 0xffff0000, v91
	v_pk_mul_f32 v[142:143], v[62:63], v[88:89]
	v_pk_mul_f32 v[88:89], v[64:65], v[90:91]
	v_pk_fma_f32 v[90:91], v[96:97], s[34:35], v[142:143] op_sel_hi:[1,0,1]
	v_pk_fma_f32 v[88:89], v[98:99], s[34:35], v[88:89] op_sel_hi:[1,0,1]
	v_add_f32_e32 v96, v90, v91
	v_add_f32_e32 v97, v88, v89
	v_add_f32_e32 v66, 0, v66
	v_add_f32_e32 v96, v96, v97
	v_add_f32_e32 v66, v96, v66
	v_cvt_f32_f16_sdwa v97, v92 dst_sel:DWORD dst_unused:UNUSED_PAD src0_sel:WORD_1
	v_cvt_f32_f16_sdwa v99, v93 dst_sel:DWORD dst_unused:UNUSED_PAD src0_sel:WORD_1
	v_cvt_f32_f16_e32 v96, v92
	v_cvt_f32_f16_e32 v98, v93
	v_lshlrev_b32_e32 v92, 16, v94
	v_and_b32_e32 v93, 0xffff0000, v94
	v_lshlrev_b32_e32 v94, 16, v95
	v_and_b32_e32 v95, 0xffff0000, v95
	v_pk_mul_f32 v[142:143], v[68:69], v[92:93]
	v_pk_mul_f32 v[92:93], v[70:71], v[94:95]
	v_pk_fma_f32 v[94:95], v[96:97], s[34:35], v[142:143] op_sel_hi:[1,0,1]
	v_pk_fma_f32 v[92:93], v[98:99], s[34:35], v[92:93] op_sel_hi:[1,0,1]
	v_add_f32_e32 v96, v94, v95
	v_add_f32_e32 v97, v92, v93
	v_add_f32_e32 v96, v96, v97
	v_add_f32_e32 v66, v96, v66
	v_cvt_f32_f16_sdwa v99, v84 dst_sel:DWORD dst_unused:UNUSED_PAD src0_sel:WORD_1
	v_cvt_f32_f16_sdwa v97, v85 dst_sel:DWORD dst_unused:UNUSED_PAD src0_sel:WORD_1
	v_cvt_f32_f16_e32 v98, v84
	v_cvt_f32_f16_e32 v96, v85
	v_lshlrev_b32_e32 v84, 16, v86
	v_and_b32_e32 v85, 0xffff0000, v86
	v_lshlrev_b32_e32 v86, 16, v87
	v_and_b32_e32 v87, 0xffff0000, v87
	v_pk_mul_f32 v[84:85], v[80:81], v[84:85]
	v_pk_mul_f32 v[86:87], v[82:83], v[86:87]
	v_pk_fma_f32 v[98:99], v[98:99], s[34:35], v[84:85] op_sel_hi:[1,0,1]
	v_pk_fma_f32 v[96:97], v[96:97], s[34:35], v[86:87] op_sel_hi:[1,0,1]
	v_add_f32_e32 v84, v98, v99
	v_add_f32_e32 v85, v96, v97
	v_add_f32_e32 v84, v84, v85
	v_add_f32_e32 v66, v84, v66
	s_nop 1
	s_ashr_i32 s11, s10, 31
	s_mov_b64 s[12:13], -1
	s_waitcnt lgkmcnt(0)
	v_add_f32_dpp v66, v66, v66 quad_perm:[1,0,3,2] row_mask:0xf bank_mask:0xf
	s_nop 1
	s_waitcnt lgkmcnt(0)
	v_add_f32_dpp v66, v66, v66 quad_perm:[2,3,0,1] row_mask:0xf bank_mask:0xf
	s_nop 1
	s_waitcnt lgkmcnt(0)
	v_add_f32_dpp v66, v66, v66 row_half_mirror row_mask:0xf bank_mask:0xf
	s_nop 1
	s_waitcnt lgkmcnt(0)
	v_add_f32_dpp v66, v66, v66 row_mirror row_mask:0xf bank_mask:0xf
	v_mov_b32_e32 v84, v66
	s_nop 1
	v_permlane16_swap_b32_e32 v84, v66
	s_waitcnt lgkmcnt(0)
	v_add_f32_e32 v66, v66, v84
	v_mov_b32_e32 v84, v66
	s_nop 1
	v_permlane32_swap_b32_e32 v84, v66
	s_waitcnt lgkmcnt(0)
; template <int MODE, bool ROUTE, int H8> ...
;     ...
;             const float mean = wave_sum(s) * (1.f / D); float s2 = 0.f;
; #pragma unroll
;             for (int jj = 0; jj < 4; ++jj) { v[jj] = v[jj] - mean; s2 += (v[jj][0] * v[jj][0] + v[jj][1] * v[jj][1]) + (v[jj][2] * v[jj][2] + v[jj][3] * v[jj][3]); }
;             const float rstd = 1.0f / sqrtf(wave_sum(s2) * (1.f / D) + LN_EPS);
;             float* orow = F.out + (size_t)row * D + 4 * F.lane;
;             unsigned long long* h8 = (unsigned long long*)(HB + (size_t)row * D + 4 * F.lane);
;             float lg[NE];
; #pragma unroll
;             for (int e = 0; e < NE; ++e) lg[e] = 0.f;
;             f32x4 hv[4];
; #pragma unroll
;             for (int jj = 0; jj < 4; ++jj) {
;                 const f32x4 xn = v[jj] * rstd * g4[jj] + b4[jj];
;                 if (xout16) __builtin_nontemporal_store(__builtin_bit_cast(u32x2, __builtin_convertvector(xn, f16x4_t)), (u32x2*)(XH + (size_t)row * D + 4 * F.lane + 256 * jj));
;                 else __builtin_nontemporal_store(xn, (f32x4*)(orow + 256 * jj));
	v_add_f32_e32 v101, v66, v84
	v_fmamk_f32 v153, v101, 0xba800000, v153
	v_fmac_f32_e32 v152, 0xba800000, v101
	v_fmamk_f32 v145, v101, 0xba800000, v145
	v_fmac_f32_e32 v144, 0xba800000, v101
	v_pk_mul_f32 v[84:85], v[144:145], v[144:145]
	v_pk_mul_f32 v[86:87], v[152:153], v[152:153]
	v_fmamk_f32 v89, v101, 0xba800000, v89
	v_pk_mov_b32 v[142:143], v[86:87], v[84:85] op_sel:[1,0]
	v_mov_b32_e32 v87, v85
	v_fmac_f32_e32 v88, 0xba800000, v101
	v_fmamk_f32 v91, v101, 0xba800000, v91
	v_fmac_f32_e32 v90, 0xba800000, v101
	v_pk_add_f32 v[84:85], v[142:143], v[86:87]
	v_pk_mul_f32 v[86:87], v[88:89], v[88:89]
	v_pk_mul_f32 v[142:143], v[90:91], v[90:91]
	v_fmac_f32_e32 v94, 0xba800000, v101
	v_pk_mov_b32 v[154:155], v[142:143], v[86:87] op_sel:[1,0]
	v_mov_b32_e32 v143, v87
	v_fmac_f32_e32 v92, 0xba800000, v101
	v_fmamk_f32 v95, v101, 0xba800000, v95
	v_mul_f32_e32 v66, v94, v94
	v_pk_add_f32 v[86:87], v[154:155], v[142:143]
	v_fmamk_f32 v93, v101, 0xba800000, v93
	v_pk_fma_f32 v[142:143], v[94:95], v[94:95], v[66:67] op_sel_hi:[1,1,0]
	v_mul_f32_e32 v66, v92, v92
	v_pk_add_f32 v[84:85], v[84:85], v[84:85] op_sel_hi:[0,1]
	v_pk_add_f32 v[86:87], v[86:87], v[86:87] op_sel_hi:[0,1]
	v_pk_fma_f32 v[154:155], v[92:93], v[92:93], v[66:67] op_sel_hi:[1,1,0]
	v_fmamk_f32 v97, v101, 0xba800000, v97
	v_fmac_f32_e32 v96, 0xba800000, v101
	v_fmamk_f32 v99, v101, 0xba800000, v99
	v_fmac_f32_e32 v98, 0xba800000, v101
	v_mul_f32_e32 v142, v98, v98
	v_mul_f32_e32 v154, v99, v99
	v_mul_f32_e32 v84, v96, v96
	v_mul_f32_e32 v86, v97, v97
	v_pk_add_f32 v[142:143], v[142:143], v[154:155]
	v_pk_add_f32 v[84:85], v[84:85], v[86:87]
	s_nop 0
	v_pk_add_f32 v[84:85], v[142:143], v[84:85]
	s_nop 0
	v_add_f32_e32 v66, v84, v85
	s_nop 1
	s_waitcnt lgkmcnt(0)
	v_add_f32_dpp v66, v66, v66 quad_perm:[1,0,3,2] row_mask:0xf bank_mask:0xf
	s_nop 1
	s_waitcnt lgkmcnt(0)
	v_add_f32_dpp v66, v66, v66 quad_perm:[2,3,0,1] row_mask:0xf bank_mask:0xf
	s_nop 1
	s_waitcnt lgkmcnt(0)
	v_add_f32_dpp v66, v66, v66 row_half_mirror row_mask:0xf bank_mask:0xf
	s_nop 1
	s_waitcnt lgkmcnt(0)
	v_add_f32_dpp v66, v66, v66 row_mirror row_mask:0xf bank_mask:0xf
	v_mov_b32_e32 v84, v66
	s_nop 1
	v_permlane16_swap_b32_e32 v84, v66
	s_waitcnt lgkmcnt(0)
	v_add_f32_e32 v66, v66, v84
	v_mov_b32_e32 v84, v66
	s_nop 1
	v_permlane32_swap_b32_e32 v84, v66
	s_waitcnt lgkmcnt(0)
	v_add_f32_e32 v66, v66, v84
	v_fmamk_f32 v66, v66, 0x3a800000, v221
	v_mul_f32_e32 v84, 0x4f800000, v66
	v_cmp_gt_f32_e32 vcc, s85, v66
	s_nop 1
	v_cndmask_b32_e32 v66, v66, v84, vcc
	v_sqrt_f32_e32 v84, v66
	s_nop 0
	v_add_u32_e32 v85, -1, v84
	v_fma_f32 v86, -v85, v84, v66
	v_cmp_ge_f32_e64 s[2:3], 0, v86
	v_add_u32_e32 v86, 1, v84
	s_nop 0
	v_cndmask_b32_e64 v85, v84, v85, s[2:3]
	v_fma_f32 v84, -v86, v84, v66
	v_cmp_lt_f32_e64 s[2:3], 0, v84
	s_nop 1
	v_cndmask_b32_e64 v84, v85, v86, s[2:3]
	v_mul_f32_e32 v85, 0x37800000, v84
	v_cndmask_b32_e32 v84, v84, v85, vcc
	v_cmp_class_f32_e32 vcc, v66, v220
	s_nop 1
	v_cndmask_b32_e32 v66, v84, v66, vcc
	v_div_scale_f32 v84, s[2:3], v66, v66, 1.0
	v_rcp_f32_e32 v85, v84
	s_lshl_b64 s[2:3], s[10:11], 11
	s_add_u32 s2, s8, s2
	s_addc_u32 s3, s9, s3
	v_fma_f32 v86, -v84, v85, 1.0
	v_fmac_f32_e32 v85, v86, v85
	v_div_scale_f32 v86, vcc, 1.0, v66, 1.0
	v_mul_f32_e32 v87, v86, v85
	v_fma_f32 v101, -v84, v87, v86
	v_fmac_f32_e32 v87, v101, v85
	v_fma_f32 v84, -v84, v87, v86
	v_div_fmas_f32 v84, v84, v85, v87
	v_div_fixup_f32 v142, v84, v66, 1.0
	v_pk_mul_f32 v[84:85], v[152:153], v[142:143] op_sel_hi:[1,0]
	v_pk_mul_f32 v[86:87], v[144:145], v[142:143] op_sel_hi:[1,0]
	v_pk_fma_f32 v[84:85], v[18:19], v[84:85], v[26:27]
	v_pk_fma_f32 v[86:87], v[20:21], v[86:87], v[28:29]
	s_and_b64 vcc, exec, s[0:1]
	v_lshlrev_b32_e32 v66, 1, v100
	s_cbranch_vccz .LBB0_1282
	v_cvt_pk_f16_f32 v145, v86, v87
	v_cvt_pk_f16_f32 v144, v84, v85
	s_mov_b64 s[12:13], 0
	global_store_dwordx2 v66, v[144:145], s[2:3] nt
